# P1+P9: dual-tile mainloop with double-buffered shared operand, own epilogues with dwordx4 stores; table conversion in phase 10
# speedup vs baseline: 1.0523x; 1.0071x over previous
.LBB0_104:
	v_lshrrev_b32_e32 v78, 3, v168
	v_lshrrev_b32_e32 v79, 4, v168
	v_xor_b32_e32 v79, v79, v168
	v_and_b32_e32 v79, 7, v79
	v_lshlrev_b32_e32 v79, 4, v79
	v_lshl_or_b32 v64, v78, 11, v79
	v_add_u32_e32 v66, 0x10000, v64
	v_add_u32_e32 v67, 0x20000, v64
	v_add_u32_e32 v77, 0x30000, v64
	s_load_dwordx2 s[90:91], s[0:1], 0xa0
	s_load_dwordx2 s[92:93], s[0:1], 0xa8
	v_lshrrev_b32_e32 v79, 6, v168
	s_nop 1
	v_readfirstlane_b32 s97, v79
	s_nop 3
	s_lshl_b32 s96, s97, 10
	s_add_u32 s96, s96, 16
	s_add_u32 s94, s66, s67
	s_cmp_lt_i32 s94, s68
	s_cselect_b32 s95, 1, 0
	s_cmp_lg_u64 s[8:9], 0
	s_cselect_b32 s95, 0, s95
	s_cmp_ge_u32 s94, 0x180
	s_cselect_b32 s97, 1, 0
	s_mul_i32 s100, s97, 0x180
	s_sub_u32 s100, s94, s100
	s_lshr_b32 s101, s100, 3
	s_and_b32 s100, s100, 7
	s_lshl_b32 s97, s97, 3
	s_add_u32 s100, s100, s97
	s_add_u32 s100, s100, s3
	s_cmp_lg_u32 s100, s60
	s_cselect_b32 s95, 0, s95
	s_cmp_eq_u32 s95, 1
	s_cselect_b32 s101, s101, s58
	s_mov_b32 s83, s101
	s_waitcnt lgkmcnt(0)
	s_lshl_b32 s101, s101, 18
	s_add_u32 s98, s92, s101
	s_addc_u32 s99, s93, 0
	s_lshl_b32 s94, s58, 18
	s_add_u32 s92, s92, s94
	s_addc_u32 s93, s93, 0
	s_lshl_b32 s94, s60, 18
	s_add_u32 s90, s90, s94
	s_addc_u32 s91, s91, 0
	s_barrier
	s_add_u32 m0, s96, 0x0
	s_nop 0
	global_load_lds_dwordx4 v64, s[90:91]
	s_add_u32 m0, s96, 0x1000
	s_nop 0
	global_load_lds_dwordx4 v66, s[90:91]
	s_add_u32 m0, s96, 0x2000
	s_nop 0
	global_load_lds_dwordx4 v67, s[90:91]
	s_add_u32 m0, s96, 0x3000
	s_nop 0
	global_load_lds_dwordx4 v77, s[90:91]
	s_add_u32 m0, s96, 0x8000
	s_nop 0
	global_load_lds_dwordx4 v64, s[92:93]
	s_add_u32 m0, s96, 0x9000
	s_nop 0
	global_load_lds_dwordx4 v66, s[92:93]
	s_add_u32 m0, s96, 0xa000
	s_nop 0
	global_load_lds_dwordx4 v67, s[92:93]
	s_add_u32 m0, s96, 0xb000
	s_nop 0
	global_load_lds_dwordx4 v77, s[92:93]
	s_add_u32 m0, s96, 0xc000
	s_nop 0
	global_load_lds_dwordx4 v64, s[98:99]
	s_add_u32 m0, s96, 0xd000
	s_nop 0
	global_load_lds_dwordx4 v66, s[98:99]
	s_add_u32 m0, s96, 0xe000
	s_nop 0
	global_load_lds_dwordx4 v67, s[98:99]
	s_add_u32 m0, s96, 0xf000
	s_nop 0
	global_load_lds_dwordx4 v77, s[98:99]
	s_add_u32 s90, s90, 0x80
	s_addc_u32 s91, s91, 0
	s_add_u32 s92, s92, 0x80
	s_addc_u32 s93, s93, 0
	s_add_u32 s98, s98, 0x80
	s_addc_u32 s99, s99, 0
	s_and_b64 vcc, exec, s[6:7]
	s_cbranch_vccnz .Lgp1_nosleep
	s_sleep 8

.Lgp1_loop:
	s_waitcnt vmcnt(0) lgkmcnt(0)
	s_barrier
	s_add_u32 m0, s96, 0x4000
	s_nop 0
	global_load_lds_dwordx4 v64, s[90:91]
	s_add_u32 m0, s96, 0x5000
	s_nop 0
	global_load_lds_dwordx4 v66, s[90:91]
	s_add_u32 m0, s96, 0x6000
	s_nop 0
	global_load_lds_dwordx4 v67, s[90:91]
	s_add_u32 m0, s96, 0x7000
	s_nop 0
	global_load_lds_dwordx4 v77, s[90:91]
	s_add_u32 s90, s90, 0x80
	s_addc_u32 s91, s91, 0
	ds_read_b128 v[216:219], v87 offset:32768
	ds_read_b128 v[220:223], v87 offset:34816
	ds_read_b128 v[224:227], v87 offset:36864
	ds_read_b128 v[228:231], v87 offset:38912
	ds_read_b128 v[248:251], v87 offset:49152
	ds_read_b128 v[252:255], v87 offset:51200
	ds_read_b128 v[68:71], v87 offset:53248
	ds_read_b128 v[72:75], v87 offset:55296
	ds_read_b128 v[232:235], v89 offset:32768
	ds_read_b128 v[236:239], v89 offset:34816
	ds_read_b128 v[240:243], v89 offset:36864
	ds_read_b128 v[244:247], v89 offset:38912
	ds_read_b128 v[96:99], v89 offset:49152
	ds_read_b128 v[100:103], v89 offset:51200
	ds_read_b128 v[104:107], v89 offset:53248
	ds_read_b128 v[112:115], v89 offset:55296
	ds_read_b128 v[184:187], v86
	ds_read_b128 v[188:191], v86 offset:2048
	ds_read_b128 v[192:195], v86 offset:4096
	ds_read_b128 v[196:199], v86 offset:6144
	s_waitcnt lgkmcnt(0)
	s_barrier
	ds_read_b128 v[200:203], v88
	ds_read_b128 v[204:207], v88 offset:2048
	ds_read_b128 v[208:211], v88 offset:4096
	ds_read_b128 v[212:215], v88 offset:6144
	s_add_u32 m0, s96, 0x8000
	v_mfma_f32_16x16x32_bf16 v[56:59], v[216:219], v[184:187], v[56:59]
	global_load_lds_dwordx4 v64, s[92:93]
	v_mfma_f32_16x16x32_bf16 v[116:119], v[248:251], v[184:187], v[116:119]
	s_add_u32 m0, s96, 0x9000
	v_mfma_f32_16x16x32_bf16 v[48:51], v[220:223], v[184:187], v[48:51]
	global_load_lds_dwordx4 v66, s[92:93]
	v_mfma_f32_16x16x32_bf16 v[120:123], v[252:255], v[184:187], v[120:123]
	s_add_u32 m0, s96, 0xa000
	v_mfma_f32_16x16x32_bf16 v[60:63], v[224:227], v[184:187], v[60:63]
	global_load_lds_dwordx4 v67, s[92:93]
	v_mfma_f32_16x16x32_bf16 v[124:127], v[68:71], v[184:187], v[124:127]
	s_add_u32 m0, s96, 0xb000
	v_mfma_f32_16x16x32_bf16 v[52:55], v[228:231], v[184:187], v[52:55]
	global_load_lds_dwordx4 v77, s[92:93]
	v_mfma_f32_16x16x32_bf16 v[128:131], v[72:75], v[184:187], v[128:131]
	s_add_u32 m0, s96, 0xc000
	v_mfma_f32_16x16x32_bf16 v[40:43], v[216:219], v[188:191], v[40:43]
	global_load_lds_dwordx4 v64, s[98:99]
	v_mfma_f32_16x16x32_bf16 v[132:135], v[248:251], v[188:191], v[132:135]
	s_add_u32 m0, s96, 0xd000
	v_mfma_f32_16x16x32_bf16 v[32:35], v[220:223], v[188:191], v[32:35]
	global_load_lds_dwordx4 v66, s[98:99]
	v_mfma_f32_16x16x32_bf16 v[136:139], v[252:255], v[188:191], v[136:139]
	s_add_u32 m0, s96, 0xe000
	v_mfma_f32_16x16x32_bf16 v[44:47], v[224:227], v[188:191], v[44:47]
	global_load_lds_dwordx4 v67, s[98:99]
	v_mfma_f32_16x16x32_bf16 v[140:143], v[68:71], v[188:191], v[140:143]
	s_add_u32 m0, s96, 0xf000
	v_mfma_f32_16x16x32_bf16 v[36:39], v[228:231], v[188:191], v[36:39]
	global_load_lds_dwordx4 v77, s[98:99]
	s_add_u32 s92, s92, 0x80
	s_addc_u32 s93, s93, 0
	s_add_u32 s98, s98, 0x80
	s_addc_u32 s99, s99, 0
	v_mfma_f32_16x16x32_bf16 v[144:147], v[72:75], v[188:191], v[144:147]
	v_mfma_f32_16x16x32_bf16 v[24:27], v[216:219], v[192:195], v[24:27]
	v_mfma_f32_16x16x32_bf16 v[148:151], v[248:251], v[192:195], v[148:151]
	v_mfma_f32_16x16x32_bf16 v[16:19], v[220:223], v[192:195], v[16:19]
	v_mfma_f32_16x16x32_bf16 v[152:155], v[252:255], v[192:195], v[152:155]
	v_mfma_f32_16x16x32_bf16 v[28:31], v[224:227], v[192:195], v[28:31]
	v_mfma_f32_16x16x32_bf16 v[156:159], v[68:71], v[192:195], v[156:159]
	v_mfma_f32_16x16x32_bf16 v[20:23], v[228:231], v[192:195], v[20:23]
	v_mfma_f32_16x16x32_bf16 v[160:163], v[72:75], v[192:195], v[160:163]
	v_mfma_f32_16x16x32_bf16 v[8:11], v[216:219], v[196:199], v[8:11]
	v_mfma_f32_16x16x32_bf16 v[164:167], v[248:251], v[196:199], v[164:167]
	v_mfma_f32_16x16x32_bf16 v[0:3], v[220:223], v[196:199], v[0:3]
	v_mfma_f32_16x16x32_bf16 v[172:175], v[252:255], v[196:199], v[172:175]
	v_mfma_f32_16x16x32_bf16 v[12:15], v[224:227], v[196:199], v[12:15]
	v_mfma_f32_16x16x32_bf16 v[176:179], v[68:71], v[196:199], v[176:179]
	v_mfma_f32_16x16x32_bf16 v[4:7], v[228:231], v[196:199], v[4:7]
	v_mfma_f32_16x16x32_bf16 v[180:183], v[72:75], v[196:199], v[180:183]
	s_waitcnt lgkmcnt(0)
	v_mfma_f32_16x16x32_bf16 v[56:59], v[232:235], v[200:203], v[56:59]
	v_mfma_f32_16x16x32_bf16 v[116:119], v[96:99], v[200:203], v[116:119]
	v_mfma_f32_16x16x32_bf16 v[48:51], v[236:239], v[200:203], v[48:51]
	v_mfma_f32_16x16x32_bf16 v[120:123], v[100:103], v[200:203], v[120:123]
	v_mfma_f32_16x16x32_bf16 v[60:63], v[240:243], v[200:203], v[60:63]
	v_mfma_f32_16x16x32_bf16 v[124:127], v[104:107], v[200:203], v[124:127]
	v_mfma_f32_16x16x32_bf16 v[52:55], v[244:247], v[200:203], v[52:55]
	v_mfma_f32_16x16x32_bf16 v[128:131], v[112:115], v[200:203], v[128:131]
	v_mfma_f32_16x16x32_bf16 v[40:43], v[232:235], v[204:207], v[40:43]
	v_mfma_f32_16x16x32_bf16 v[132:135], v[96:99], v[204:207], v[132:135]
	v_mfma_f32_16x16x32_bf16 v[32:35], v[236:239], v[204:207], v[32:35]
	v_mfma_f32_16x16x32_bf16 v[136:139], v[100:103], v[204:207], v[136:139]
	v_mfma_f32_16x16x32_bf16 v[44:47], v[240:243], v[204:207], v[44:47]
	v_mfma_f32_16x16x32_bf16 v[140:143], v[104:107], v[204:207], v[140:143]
	v_mfma_f32_16x16x32_bf16 v[36:39], v[244:247], v[204:207], v[36:39]
	v_mfma_f32_16x16x32_bf16 v[144:147], v[112:115], v[204:207], v[144:147]
	v_mfma_f32_16x16x32_bf16 v[24:27], v[232:235], v[208:211], v[24:27]
	v_mfma_f32_16x16x32_bf16 v[148:151], v[96:99], v[208:211], v[148:151]
	v_mfma_f32_16x16x32_bf16 v[16:19], v[236:239], v[208:211], v[16:19]
	v_mfma_f32_16x16x32_bf16 v[152:155], v[100:103], v[208:211], v[152:155]
	v_mfma_f32_16x16x32_bf16 v[28:31], v[240:243], v[208:211], v[28:31]
	v_mfma_f32_16x16x32_bf16 v[156:159], v[104:107], v[208:211], v[156:159]
	v_mfma_f32_16x16x32_bf16 v[20:23], v[244:247], v[208:211], v[20:23]
	v_mfma_f32_16x16x32_bf16 v[160:163], v[112:115], v[208:211], v[160:163]
	v_mfma_f32_16x16x32_bf16 v[8:11], v[232:235], v[212:215], v[8:11]
	v_mfma_f32_16x16x32_bf16 v[164:167], v[96:99], v[212:215], v[164:167]
	v_mfma_f32_16x16x32_bf16 v[0:3], v[236:239], v[212:215], v[0:3]
	v_mfma_f32_16x16x32_bf16 v[172:175], v[100:103], v[212:215], v[172:175]
	v_mfma_f32_16x16x32_bf16 v[12:15], v[240:243], v[212:215], v[12:15]
	v_mfma_f32_16x16x32_bf16 v[176:179], v[104:107], v[212:215], v[176:179]
	v_mfma_f32_16x16x32_bf16 v[4:7], v[244:247], v[212:215], v[4:7]
	v_mfma_f32_16x16x32_bf16 v[180:183], v[112:115], v[212:215], v[180:183]
	s_waitcnt vmcnt(0) lgkmcnt(0)
	s_barrier
	s_cmp_eq_u32 s94, 7
	s_cbranch_scc1 .Lgp1_noS
	s_add_u32 m0, s96, 0x0
	s_nop 0
	global_load_lds_dwordx4 v64, s[90:91]
	s_add_u32 m0, s96, 0x1000
	s_nop 0
	global_load_lds_dwordx4 v66, s[90:91]
	s_add_u32 m0, s96, 0x2000
	s_nop 0
	global_load_lds_dwordx4 v67, s[90:91]
	s_add_u32 m0, s96, 0x3000
	s_nop 0
	global_load_lds_dwordx4 v77, s[90:91]
	s_add_u32 s90, s90, 0x80
	s_addc_u32 s91, s91, 0
.Lgp1_noS:
	ds_read_b128 v[216:219], v87 offset:32768
	ds_read_b128 v[220:223], v87 offset:34816
	ds_read_b128 v[224:227], v87 offset:36864
	ds_read_b128 v[228:231], v87 offset:38912
	ds_read_b128 v[248:251], v87 offset:49152
	ds_read_b128 v[252:255], v87 offset:51200
	ds_read_b128 v[68:71], v87 offset:53248
	ds_read_b128 v[72:75], v87 offset:55296
	ds_read_b128 v[232:235], v89 offset:32768
	ds_read_b128 v[236:239], v89 offset:34816
	ds_read_b128 v[240:243], v89 offset:36864
	ds_read_b128 v[244:247], v89 offset:38912
	ds_read_b128 v[96:99], v89 offset:49152
	ds_read_b128 v[100:103], v89 offset:51200
	ds_read_b128 v[104:107], v89 offset:53248
	ds_read_b128 v[112:115], v89 offset:55296
	ds_read_b128 v[184:187], v86 offset:16384
	ds_read_b128 v[188:191], v86 offset:18432
	ds_read_b128 v[192:195], v86 offset:20480
	ds_read_b128 v[196:199], v86 offset:22528
	s_waitcnt lgkmcnt(0)
	s_barrier
	ds_read_b128 v[200:203], v88 offset:16384
	ds_read_b128 v[204:207], v88 offset:18432
	ds_read_b128 v[208:211], v88 offset:20480
	ds_read_b128 v[212:215], v88 offset:22528
	s_cmp_eq_u32 s94, 7
	s_cbranch_scc1 .Lgp1_last
	s_add_u32 m0, s96, 0x8000
	v_mfma_f32_16x16x32_bf16 v[56:59], v[216:219], v[184:187], v[56:59]
	global_load_lds_dwordx4 v64, s[92:93]
	v_mfma_f32_16x16x32_bf16 v[116:119], v[248:251], v[184:187], v[116:119]
	s_add_u32 m0, s96, 0x9000
	v_mfma_f32_16x16x32_bf16 v[48:51], v[220:223], v[184:187], v[48:51]
	global_load_lds_dwordx4 v66, s[92:93]
	v_mfma_f32_16x16x32_bf16 v[120:123], v[252:255], v[184:187], v[120:123]
	s_add_u32 m0, s96, 0xa000
	v_mfma_f32_16x16x32_bf16 v[60:63], v[224:227], v[184:187], v[60:63]
	global_load_lds_dwordx4 v67, s[92:93]
	v_mfma_f32_16x16x32_bf16 v[124:127], v[68:71], v[184:187], v[124:127]
	s_add_u32 m0, s96, 0xb000
	v_mfma_f32_16x16x32_bf16 v[52:55], v[228:231], v[184:187], v[52:55]
	global_load_lds_dwordx4 v77, s[92:93]
	v_mfma_f32_16x16x32_bf16 v[128:131], v[72:75], v[184:187], v[128:131]
	s_add_u32 m0, s96, 0xc000
	v_mfma_f32_16x16x32_bf16 v[40:43], v[216:219], v[188:191], v[40:43]
	global_load_lds_dwordx4 v64, s[98:99]
	v_mfma_f32_16x16x32_bf16 v[132:135], v[248:251], v[188:191], v[132:135]
	s_add_u32 m0, s96, 0xd000
	v_mfma_f32_16x16x32_bf16 v[32:35], v[220:223], v[188:191], v[32:35]
	global_load_lds_dwordx4 v66, s[98:99]
	v_mfma_f32_16x16x32_bf16 v[136:139], v[252:255], v[188:191], v[136:139]
	s_add_u32 m0, s96, 0xe000
	v_mfma_f32_16x16x32_bf16 v[44:47], v[224:227], v[188:191], v[44:47]
	global_load_lds_dwordx4 v67, s[98:99]
	v_mfma_f32_16x16x32_bf16 v[140:143], v[68:71], v[188:191], v[140:143]
	s_add_u32 m0, s96, 0xf000
	v_mfma_f32_16x16x32_bf16 v[36:39], v[228:231], v[188:191], v[36:39]
	global_load_lds_dwordx4 v77, s[98:99]
	s_add_u32 s92, s92, 0x80
	s_addc_u32 s93, s93, 0
	s_add_u32 s98, s98, 0x80
	s_addc_u32 s99, s99, 0
	v_mfma_f32_16x16x32_bf16 v[144:147], v[72:75], v[188:191], v[144:147]
	v_mfma_f32_16x16x32_bf16 v[24:27], v[216:219], v[192:195], v[24:27]
	v_mfma_f32_16x16x32_bf16 v[148:151], v[248:251], v[192:195], v[148:151]
	v_mfma_f32_16x16x32_bf16 v[16:19], v[220:223], v[192:195], v[16:19]
	v_mfma_f32_16x16x32_bf16 v[152:155], v[252:255], v[192:195], v[152:155]
	v_mfma_f32_16x16x32_bf16 v[28:31], v[224:227], v[192:195], v[28:31]
	v_mfma_f32_16x16x32_bf16 v[156:159], v[68:71], v[192:195], v[156:159]
	v_mfma_f32_16x16x32_bf16 v[20:23], v[228:231], v[192:195], v[20:23]
	v_mfma_f32_16x16x32_bf16 v[160:163], v[72:75], v[192:195], v[160:163]
	v_mfma_f32_16x16x32_bf16 v[8:11], v[216:219], v[196:199], v[8:11]
	v_mfma_f32_16x16x32_bf16 v[164:167], v[248:251], v[196:199], v[164:167]
	v_mfma_f32_16x16x32_bf16 v[0:3], v[220:223], v[196:199], v[0:3]
	v_mfma_f32_16x16x32_bf16 v[172:175], v[252:255], v[196:199], v[172:175]
	v_mfma_f32_16x16x32_bf16 v[12:15], v[224:227], v[196:199], v[12:15]
	v_mfma_f32_16x16x32_bf16 v[176:179], v[68:71], v[196:199], v[176:179]
	v_mfma_f32_16x16x32_bf16 v[4:7], v[228:231], v[196:199], v[4:7]
	v_mfma_f32_16x16x32_bf16 v[180:183], v[72:75], v[196:199], v[180:183]
	s_waitcnt lgkmcnt(0)
	v_mfma_f32_16x16x32_bf16 v[56:59], v[232:235], v[200:203], v[56:59]
	v_mfma_f32_16x16x32_bf16 v[116:119], v[96:99], v[200:203], v[116:119]
	v_mfma_f32_16x16x32_bf16 v[48:51], v[236:239], v[200:203], v[48:51]
	v_mfma_f32_16x16x32_bf16 v[120:123], v[100:103], v[200:203], v[120:123]
	v_mfma_f32_16x16x32_bf16 v[60:63], v[240:243], v[200:203], v[60:63]
	v_mfma_f32_16x16x32_bf16 v[124:127], v[104:107], v[200:203], v[124:127]
	v_mfma_f32_16x16x32_bf16 v[52:55], v[244:247], v[200:203], v[52:55]
	v_mfma_f32_16x16x32_bf16 v[128:131], v[112:115], v[200:203], v[128:131]
	v_mfma_f32_16x16x32_bf16 v[40:43], v[232:235], v[204:207], v[40:43]
	v_mfma_f32_16x16x32_bf16 v[132:135], v[96:99], v[204:207], v[132:135]
	v_mfma_f32_16x16x32_bf16 v[32:35], v[236:239], v[204:207], v[32:35]
	v_mfma_f32_16x16x32_bf16 v[136:139], v[100:103], v[204:207], v[136:139]
	v_mfma_f32_16x16x32_bf16 v[44:47], v[240:243], v[204:207], v[44:47]
	v_mfma_f32_16x16x32_bf16 v[140:143], v[104:107], v[204:207], v[140:143]
	v_mfma_f32_16x16x32_bf16 v[36:39], v[244:247], v[204:207], v[36:39]
	v_mfma_f32_16x16x32_bf16 v[144:147], v[112:115], v[204:207], v[144:147]
	v_mfma_f32_16x16x32_bf16 v[24:27], v[232:235], v[208:211], v[24:27]
	v_mfma_f32_16x16x32_bf16 v[148:151], v[96:99], v[208:211], v[148:151]
	v_mfma_f32_16x16x32_bf16 v[16:19], v[236:239], v[208:211], v[16:19]
	v_mfma_f32_16x16x32_bf16 v[152:155], v[100:103], v[208:211], v[152:155]
	v_mfma_f32_16x16x32_bf16 v[28:31], v[240:243], v[208:211], v[28:31]
	v_mfma_f32_16x16x32_bf16 v[156:159], v[104:107], v[208:211], v[156:159]
	v_mfma_f32_16x16x32_bf16 v[20:23], v[244:247], v[208:211], v[20:23]
	v_mfma_f32_16x16x32_bf16 v[160:163], v[112:115], v[208:211], v[160:163]
	v_mfma_f32_16x16x32_bf16 v[8:11], v[232:235], v[212:215], v[8:11]
	v_mfma_f32_16x16x32_bf16 v[164:167], v[96:99], v[212:215], v[164:167]
	v_mfma_f32_16x16x32_bf16 v[0:3], v[236:239], v[212:215], v[0:3]
	v_mfma_f32_16x16x32_bf16 v[172:175], v[100:103], v[212:215], v[172:175]
	v_mfma_f32_16x16x32_bf16 v[12:15], v[240:243], v[212:215], v[12:15]
	v_mfma_f32_16x16x32_bf16 v[176:179], v[104:107], v[212:215], v[176:179]
	v_mfma_f32_16x16x32_bf16 v[4:7], v[244:247], v[212:215], v[4:7]
	v_mfma_f32_16x16x32_bf16 v[180:183], v[112:115], v[212:215], v[180:183]
	s_add_u32 s94, s94, 1
	s_branch .Lgp1_loop
.Lgp1_last:
	v_mfma_f32_16x16x32_bf16 v[56:59], v[216:219], v[184:187], v[56:59]
	v_mfma_f32_16x16x32_bf16 v[116:119], v[248:251], v[184:187], v[116:119]
	v_mfma_f32_16x16x32_bf16 v[48:51], v[220:223], v[184:187], v[48:51]
	v_mfma_f32_16x16x32_bf16 v[120:123], v[252:255], v[184:187], v[120:123]
	v_mfma_f32_16x16x32_bf16 v[60:63], v[224:227], v[184:187], v[60:63]
	v_mfma_f32_16x16x32_bf16 v[124:127], v[68:71], v[184:187], v[124:127]
	v_mfma_f32_16x16x32_bf16 v[52:55], v[228:231], v[184:187], v[52:55]
	v_mfma_f32_16x16x32_bf16 v[128:131], v[72:75], v[184:187], v[128:131]
	v_mfma_f32_16x16x32_bf16 v[40:43], v[216:219], v[188:191], v[40:43]
	v_mfma_f32_16x16x32_bf16 v[132:135], v[248:251], v[188:191], v[132:135]
	v_mfma_f32_16x16x32_bf16 v[32:35], v[220:223], v[188:191], v[32:35]
	v_mfma_f32_16x16x32_bf16 v[136:139], v[252:255], v[188:191], v[136:139]
	v_mfma_f32_16x16x32_bf16 v[44:47], v[224:227], v[188:191], v[44:47]
	v_mfma_f32_16x16x32_bf16 v[140:143], v[68:71], v[188:191], v[140:143]
	v_mfma_f32_16x16x32_bf16 v[36:39], v[228:231], v[188:191], v[36:39]
	v_mfma_f32_16x16x32_bf16 v[144:147], v[72:75], v[188:191], v[144:147]
	v_mfma_f32_16x16x32_bf16 v[24:27], v[216:219], v[192:195], v[24:27]
	v_mfma_f32_16x16x32_bf16 v[148:151], v[248:251], v[192:195], v[148:151]
	v_mfma_f32_16x16x32_bf16 v[16:19], v[220:223], v[192:195], v[16:19]
	v_mfma_f32_16x16x32_bf16 v[152:155], v[252:255], v[192:195], v[152:155]
	v_mfma_f32_16x16x32_bf16 v[28:31], v[224:227], v[192:195], v[28:31]
	v_mfma_f32_16x16x32_bf16 v[156:159], v[68:71], v[192:195], v[156:159]
	v_mfma_f32_16x16x32_bf16 v[20:23], v[228:231], v[192:195], v[20:23]
	v_mfma_f32_16x16x32_bf16 v[160:163], v[72:75], v[192:195], v[160:163]
	v_mfma_f32_16x16x32_bf16 v[8:11], v[216:219], v[196:199], v[8:11]
	v_mfma_f32_16x16x32_bf16 v[164:167], v[248:251], v[196:199], v[164:167]
	v_mfma_f32_16x16x32_bf16 v[0:3], v[220:223], v[196:199], v[0:3]
	v_mfma_f32_16x16x32_bf16 v[172:175], v[252:255], v[196:199], v[172:175]
	v_mfma_f32_16x16x32_bf16 v[12:15], v[224:227], v[196:199], v[12:15]
	v_mfma_f32_16x16x32_bf16 v[176:179], v[68:71], v[196:199], v[176:179]
	v_mfma_f32_16x16x32_bf16 v[4:7], v[228:231], v[196:199], v[4:7]
	v_mfma_f32_16x16x32_bf16 v[180:183], v[72:75], v[196:199], v[180:183]
	s_waitcnt lgkmcnt(0)
	v_mfma_f32_16x16x32_bf16 v[56:59], v[232:235], v[200:203], v[56:59]
	v_mfma_f32_16x16x32_bf16 v[116:119], v[96:99], v[200:203], v[116:119]
	v_mfma_f32_16x16x32_bf16 v[48:51], v[236:239], v[200:203], v[48:51]
	v_mfma_f32_16x16x32_bf16 v[120:123], v[100:103], v[200:203], v[120:123]
	v_mfma_f32_16x16x32_bf16 v[60:63], v[240:243], v[200:203], v[60:63]
	v_mfma_f32_16x16x32_bf16 v[124:127], v[104:107], v[200:203], v[124:127]
	v_mfma_f32_16x16x32_bf16 v[52:55], v[244:247], v[200:203], v[52:55]
	v_mfma_f32_16x16x32_bf16 v[128:131], v[112:115], v[200:203], v[128:131]
	v_mfma_f32_16x16x32_bf16 v[40:43], v[232:235], v[204:207], v[40:43]
	v_mfma_f32_16x16x32_bf16 v[132:135], v[96:99], v[204:207], v[132:135]
	v_mfma_f32_16x16x32_bf16 v[32:35], v[236:239], v[204:207], v[32:35]
	v_mfma_f32_16x16x32_bf16 v[136:139], v[100:103], v[204:207], v[136:139]
	v_mfma_f32_16x16x32_bf16 v[44:47], v[240:243], v[204:207], v[44:47]
	v_mfma_f32_16x16x32_bf16 v[140:143], v[104:107], v[204:207], v[140:143]
	v_mfma_f32_16x16x32_bf16 v[36:39], v[244:247], v[204:207], v[36:39]
	v_mfma_f32_16x16x32_bf16 v[144:147], v[112:115], v[204:207], v[144:147]
	v_mfma_f32_16x16x32_bf16 v[24:27], v[232:235], v[208:211], v[24:27]
	v_mfma_f32_16x16x32_bf16 v[148:151], v[96:99], v[208:211], v[148:151]
	v_mfma_f32_16x16x32_bf16 v[16:19], v[236:239], v[208:211], v[16:19]
	v_mfma_f32_16x16x32_bf16 v[152:155], v[100:103], v[208:211], v[152:155]
	v_mfma_f32_16x16x32_bf16 v[28:31], v[240:243], v[208:211], v[28:31]
	v_mfma_f32_16x16x32_bf16 v[156:159], v[104:107], v[208:211], v[156:159]
	v_mfma_f32_16x16x32_bf16 v[20:23], v[244:247], v[208:211], v[20:23]
	v_mfma_f32_16x16x32_bf16 v[160:163], v[112:115], v[208:211], v[160:163]
	v_mfma_f32_16x16x32_bf16 v[8:11], v[232:235], v[212:215], v[8:11]
	v_mfma_f32_16x16x32_bf16 v[164:167], v[96:99], v[212:215], v[164:167]
	v_mfma_f32_16x16x32_bf16 v[0:3], v[236:239], v[212:215], v[0:3]
	v_mfma_f32_16x16x32_bf16 v[172:175], v[100:103], v[212:215], v[172:175]
	v_mfma_f32_16x16x32_bf16 v[12:15], v[240:243], v[212:215], v[12:15]
	v_mfma_f32_16x16x32_bf16 v[176:179], v[104:107], v[212:215], v[176:179]
	v_mfma_f32_16x16x32_bf16 v[4:7], v[244:247], v[212:215], v[4:7]
	v_mfma_f32_16x16x32_bf16 v[180:183], v[112:115], v[212:215], v[180:183]
	s_nop 7
	s_nop 3
	v_lshrrev_b32_e32 v212, 1, v168
	v_and_b32_e32 v212, 0x1c0, v212
	v_and_b32_e32 v213, 15, v168
	v_or_b32_e32 v212, v212, v213
	v_lshl_add_u32 v212, s60, 7, v212
	v_lshlrev_b32_e32 v212, 11, v212
	v_bfe_u32 v213, v168, 4, 2
	v_lshlrev_b32_e32 v209, 3, v213
	v_and_b32_e32 v213, 1, v213
	v_mul_u32_u24_e32 v213, 24, v213
	v_add3_u32 v212, v212, v213, v209
	v_bfe_u32 v213, v168, 6, 1
	s_cmp_lt_u32 s58, 16
	s_cbranch_scc1 .Lep1a_B
	s_sub_u32 s87, s58, 16
	s_lshr_b32 s88, s87, 3
	s_and_b32 s87, s87, 7
	s_lshl_b32 s89, s88, 3
	s_add_u32 s89, s89, 0xe0
	s_load_dwordx2 s[84:85], s[0:1], s89
	s_cmp_eq_u32 s88, 1
	s_cselect_b32 s88, 1, 0
	s_cmp_lt_u32 s87, 4
	s_cselect_b32 s88, s88, 0
	s_mov_b32 s86, 1.0
	s_cmp_eq_u32 s88, 1
	s_cselect_b32 s86, 0x3db504f3, s86
	s_lshl_b32 s87, s87, 8
	v_lshl_add_u32 v208, v213, 7, v212
	v_add_u32_e32 v208, s87, v208
	v_add_u32_e32 v209, 0x8000, v208
	v_add_u32_e32 v210, 0x10000, v208
	v_add_u32_e32 v211, 0x18000, v208
	s_waitcnt lgkmcnt(0)
	v_mul_f32_e32 v184, s86, v56
	v_mul_f32_e32 v185, s86, v57
	v_mul_f32_e32 v186, s86, v58
	v_mul_f32_e32 v187, s86, v59
	v_mul_f32_e32 v188, s86, v48
	v_mul_f32_e32 v189, s86, v49
	v_mul_f32_e32 v190, s86, v50
	v_mul_f32_e32 v191, s86, v51
	v_and_b32_sdwa v192, v184, v110 dst_sel:DWORD dst_unused:UNUSED_PAD src0_sel:WORD_1 src1_sel:DWORD
	v_and_b32_sdwa v193, v185, v110 dst_sel:DWORD dst_unused:UNUSED_PAD src0_sel:WORD_1 src1_sel:DWORD
	v_and_b32_sdwa v194, v186, v110 dst_sel:DWORD dst_unused:UNUSED_PAD src0_sel:WORD_1 src1_sel:DWORD
	v_and_b32_sdwa v195, v187, v110 dst_sel:DWORD dst_unused:UNUSED_PAD src0_sel:WORD_1 src1_sel:DWORD
	v_and_b32_sdwa v196, v188, v110 dst_sel:DWORD dst_unused:UNUSED_PAD src0_sel:WORD_1 src1_sel:DWORD
	v_and_b32_sdwa v197, v189, v110 dst_sel:DWORD dst_unused:UNUSED_PAD src0_sel:WORD_1 src1_sel:DWORD
	v_and_b32_sdwa v198, v190, v110 dst_sel:DWORD dst_unused:UNUSED_PAD src0_sel:WORD_1 src1_sel:DWORD
	v_and_b32_sdwa v199, v191, v110 dst_sel:DWORD dst_unused:UNUSED_PAD src0_sel:WORD_1 src1_sel:DWORD
	v_add3_u32 v184, v184, v192, s69
	v_add3_u32 v185, v185, v193, s69
	v_add3_u32 v186, v186, v194, s69
	v_add3_u32 v187, v187, v195, s69
	v_add3_u32 v188, v188, v196, s69
	v_add3_u32 v189, v189, v197, s69
	v_add3_u32 v190, v190, v198, s69
	v_add3_u32 v191, v191, v199, s69
	v_and_b32_e32 v185, 0xffff0000, v185
	v_and_b32_e32 v187, 0xffff0000, v187
	v_and_b32_e32 v189, 0xffff0000, v189
	v_and_b32_e32 v191, 0xffff0000, v191
	v_or_b32_sdwa v200, v185, v184 dst_sel:DWORD dst_unused:UNUSED_PAD src0_sel:DWORD src1_sel:WORD_1
	v_or_b32_sdwa v201, v187, v186 dst_sel:DWORD dst_unused:UNUSED_PAD src0_sel:DWORD src1_sel:WORD_1
	v_or_b32_sdwa v202, v189, v188 dst_sel:DWORD dst_unused:UNUSED_PAD src0_sel:DWORD src1_sel:WORD_1
	v_or_b32_sdwa v203, v191, v190 dst_sel:DWORD dst_unused:UNUSED_PAD src0_sel:DWORD src1_sel:WORD_1
	s_nop 1
	v_permlane16_swap_b32_e32 v200, v202
	v_permlane16_swap_b32_e32 v201, v203
	global_store_dwordx4 v208, v[200:203], s[84:85]
	v_mul_f32_e32 v184, s86, v60
	v_mul_f32_e32 v185, s86, v61
	v_mul_f32_e32 v186, s86, v62
	v_mul_f32_e32 v187, s86, v63
	v_mul_f32_e32 v188, s86, v52
	v_mul_f32_e32 v189, s86, v53
	v_mul_f32_e32 v190, s86, v54
	v_mul_f32_e32 v191, s86, v55
	v_and_b32_sdwa v192, v184, v110 dst_sel:DWORD dst_unused:UNUSED_PAD src0_sel:WORD_1 src1_sel:DWORD
	v_and_b32_sdwa v193, v185, v110 dst_sel:DWORD dst_unused:UNUSED_PAD src0_sel:WORD_1 src1_sel:DWORD
	v_and_b32_sdwa v194, v186, v110 dst_sel:DWORD dst_unused:UNUSED_PAD src0_sel:WORD_1 src1_sel:DWORD
	v_and_b32_sdwa v195, v187, v110 dst_sel:DWORD dst_unused:UNUSED_PAD src0_sel:WORD_1 src1_sel:DWORD
	v_and_b32_sdwa v196, v188, v110 dst_sel:DWORD dst_unused:UNUSED_PAD src0_sel:WORD_1 src1_sel:DWORD
	v_and_b32_sdwa v197, v189, v110 dst_sel:DWORD dst_unused:UNUSED_PAD src0_sel:WORD_1 src1_sel:DWORD
	v_and_b32_sdwa v198, v190, v110 dst_sel:DWORD dst_unused:UNUSED_PAD src0_sel:WORD_1 src1_sel:DWORD
	v_and_b32_sdwa v199, v191, v110 dst_sel:DWORD dst_unused:UNUSED_PAD src0_sel:WORD_1 src1_sel:DWORD
	v_add3_u32 v184, v184, v192, s69
	v_add3_u32 v185, v185, v193, s69
	v_add3_u32 v186, v186, v194, s69
	v_add3_u32 v187, v187, v195, s69
	v_add3_u32 v188, v188, v196, s69
	v_add3_u32 v189, v189, v197, s69
	v_add3_u32 v190, v190, v198, s69
	v_add3_u32 v191, v191, v199, s69
	v_and_b32_e32 v185, 0xffff0000, v185
	v_and_b32_e32 v187, 0xffff0000, v187
	v_and_b32_e32 v189, 0xffff0000, v189
	v_and_b32_e32 v191, 0xffff0000, v191
	v_or_b32_sdwa v204, v185, v184 dst_sel:DWORD dst_unused:UNUSED_PAD src0_sel:DWORD src1_sel:WORD_1
	v_or_b32_sdwa v205, v187, v186 dst_sel:DWORD dst_unused:UNUSED_PAD src0_sel:DWORD src1_sel:WORD_1
	v_or_b32_sdwa v206, v189, v188 dst_sel:DWORD dst_unused:UNUSED_PAD src0_sel:DWORD src1_sel:WORD_1
	v_or_b32_sdwa v207, v191, v190 dst_sel:DWORD dst_unused:UNUSED_PAD src0_sel:DWORD src1_sel:WORD_1
	s_nop 1
	v_permlane16_swap_b32_e32 v204, v206
	v_permlane16_swap_b32_e32 v205, v207
	global_store_dwordx4 v208, v[204:207], s[84:85] offset:64
	v_mul_f32_e32 v184, s86, v40
	v_mul_f32_e32 v185, s86, v41
	v_mul_f32_e32 v186, s86, v42
	v_mul_f32_e32 v187, s86, v43
	v_mul_f32_e32 v188, s86, v32
	v_mul_f32_e32 v189, s86, v33
	v_mul_f32_e32 v190, s86, v34
	v_mul_f32_e32 v191, s86, v35
	v_and_b32_sdwa v192, v184, v110 dst_sel:DWORD dst_unused:UNUSED_PAD src0_sel:WORD_1 src1_sel:DWORD
	v_and_b32_sdwa v193, v185, v110 dst_sel:DWORD dst_unused:UNUSED_PAD src0_sel:WORD_1 src1_sel:DWORD
	v_and_b32_sdwa v194, v186, v110 dst_sel:DWORD dst_unused:UNUSED_PAD src0_sel:WORD_1 src1_sel:DWORD
	v_and_b32_sdwa v195, v187, v110 dst_sel:DWORD dst_unused:UNUSED_PAD src0_sel:WORD_1 src1_sel:DWORD
	v_and_b32_sdwa v196, v188, v110 dst_sel:DWORD dst_unused:UNUSED_PAD src0_sel:WORD_1 src1_sel:DWORD
	v_and_b32_sdwa v197, v189, v110 dst_sel:DWORD dst_unused:UNUSED_PAD src0_sel:WORD_1 src1_sel:DWORD
	v_and_b32_sdwa v198, v190, v110 dst_sel:DWORD dst_unused:UNUSED_PAD src0_sel:WORD_1 src1_sel:DWORD
	v_and_b32_sdwa v199, v191, v110 dst_sel:DWORD dst_unused:UNUSED_PAD src0_sel:WORD_1 src1_sel:DWORD
	v_add3_u32 v184, v184, v192, s69
	v_add3_u32 v185, v185, v193, s69
	v_add3_u32 v186, v186, v194, s69
	v_add3_u32 v187, v187, v195, s69
	v_add3_u32 v188, v188, v196, s69
	v_add3_u32 v189, v189, v197, s69
	v_add3_u32 v190, v190, v198, s69
	v_add3_u32 v191, v191, v199, s69
	v_and_b32_e32 v185, 0xffff0000, v185
	v_and_b32_e32 v187, 0xffff0000, v187
	v_and_b32_e32 v189, 0xffff0000, v189
	v_and_b32_e32 v191, 0xffff0000, v191
	v_or_b32_sdwa v200, v185, v184 dst_sel:DWORD dst_unused:UNUSED_PAD src0_sel:DWORD src1_sel:WORD_1
	v_or_b32_sdwa v201, v187, v186 dst_sel:DWORD dst_unused:UNUSED_PAD src0_sel:DWORD src1_sel:WORD_1
	v_or_b32_sdwa v202, v189, v188 dst_sel:DWORD dst_unused:UNUSED_PAD src0_sel:DWORD src1_sel:WORD_1
	v_or_b32_sdwa v203, v191, v190 dst_sel:DWORD dst_unused:UNUSED_PAD src0_sel:DWORD src1_sel:WORD_1
	s_nop 1
	v_permlane16_swap_b32_e32 v200, v202
	v_permlane16_swap_b32_e32 v201, v203
	global_store_dwordx4 v209, v[200:203], s[84:85]
	v_mul_f32_e32 v184, s86, v44
	v_mul_f32_e32 v185, s86, v45
	v_mul_f32_e32 v186, s86, v46
	v_mul_f32_e32 v187, s86, v47
	v_mul_f32_e32 v188, s86, v36
	v_mul_f32_e32 v189, s86, v37
	v_mul_f32_e32 v190, s86, v38
	v_mul_f32_e32 v191, s86, v39
	v_and_b32_sdwa v192, v184, v110 dst_sel:DWORD dst_unused:UNUSED_PAD src0_sel:WORD_1 src1_sel:DWORD
	v_and_b32_sdwa v193, v185, v110 dst_sel:DWORD dst_unused:UNUSED_PAD src0_sel:WORD_1 src1_sel:DWORD
	v_and_b32_sdwa v194, v186, v110 dst_sel:DWORD dst_unused:UNUSED_PAD src0_sel:WORD_1 src1_sel:DWORD
	v_and_b32_sdwa v195, v187, v110 dst_sel:DWORD dst_unused:UNUSED_PAD src0_sel:WORD_1 src1_sel:DWORD
	v_and_b32_sdwa v196, v188, v110 dst_sel:DWORD dst_unused:UNUSED_PAD src0_sel:WORD_1 src1_sel:DWORD
	v_and_b32_sdwa v197, v189, v110 dst_sel:DWORD dst_unused:UNUSED_PAD src0_sel:WORD_1 src1_sel:DWORD
	v_and_b32_sdwa v198, v190, v110 dst_sel:DWORD dst_unused:UNUSED_PAD src0_sel:WORD_1 src1_sel:DWORD
	v_and_b32_sdwa v199, v191, v110 dst_sel:DWORD dst_unused:UNUSED_PAD src0_sel:WORD_1 src1_sel:DWORD
	v_add3_u32 v184, v184, v192, s69
	v_add3_u32 v185, v185, v193, s69
	v_add3_u32 v186, v186, v194, s69
	v_add3_u32 v187, v187, v195, s69
	v_add3_u32 v188, v188, v196, s69
	v_add3_u32 v189, v189, v197, s69
	v_add3_u32 v190, v190, v198, s69
	v_add3_u32 v191, v191, v199, s69
	v_and_b32_e32 v185, 0xffff0000, v185
	v_and_b32_e32 v187, 0xffff0000, v187
	v_and_b32_e32 v189, 0xffff0000, v189
	v_and_b32_e32 v191, 0xffff0000, v191
	v_or_b32_sdwa v204, v185, v184 dst_sel:DWORD dst_unused:UNUSED_PAD src0_sel:DWORD src1_sel:WORD_1
	v_or_b32_sdwa v205, v187, v186 dst_sel:DWORD dst_unused:UNUSED_PAD src0_sel:DWORD src1_sel:WORD_1
	v_or_b32_sdwa v206, v189, v188 dst_sel:DWORD dst_unused:UNUSED_PAD src0_sel:DWORD src1_sel:WORD_1
	v_or_b32_sdwa v207, v191, v190 dst_sel:DWORD dst_unused:UNUSED_PAD src0_sel:DWORD src1_sel:WORD_1
	s_nop 1
	v_permlane16_swap_b32_e32 v204, v206
	v_permlane16_swap_b32_e32 v205, v207
	global_store_dwordx4 v209, v[204:207], s[84:85] offset:64
	v_mul_f32_e32 v184, s86, v24
	v_mul_f32_e32 v185, s86, v25
	v_mul_f32_e32 v186, s86, v26
	v_mul_f32_e32 v187, s86, v27
	v_mul_f32_e32 v188, s86, v16
	v_mul_f32_e32 v189, s86, v17
	v_mul_f32_e32 v190, s86, v18
	v_mul_f32_e32 v191, s86, v19
	v_and_b32_sdwa v192, v184, v110 dst_sel:DWORD dst_unused:UNUSED_PAD src0_sel:WORD_1 src1_sel:DWORD
	v_and_b32_sdwa v193, v185, v110 dst_sel:DWORD dst_unused:UNUSED_PAD src0_sel:WORD_1 src1_sel:DWORD
	v_and_b32_sdwa v194, v186, v110 dst_sel:DWORD dst_unused:UNUSED_PAD src0_sel:WORD_1 src1_sel:DWORD
	v_and_b32_sdwa v195, v187, v110 dst_sel:DWORD dst_unused:UNUSED_PAD src0_sel:WORD_1 src1_sel:DWORD
	v_and_b32_sdwa v196, v188, v110 dst_sel:DWORD dst_unused:UNUSED_PAD src0_sel:WORD_1 src1_sel:DWORD
	v_and_b32_sdwa v197, v189, v110 dst_sel:DWORD dst_unused:UNUSED_PAD src0_sel:WORD_1 src1_sel:DWORD
	v_and_b32_sdwa v198, v190, v110 dst_sel:DWORD dst_unused:UNUSED_PAD src0_sel:WORD_1 src1_sel:DWORD
	v_and_b32_sdwa v199, v191, v110 dst_sel:DWORD dst_unused:UNUSED_PAD src0_sel:WORD_1 src1_sel:DWORD
	v_add3_u32 v184, v184, v192, s69
	v_add3_u32 v185, v185, v193, s69
	v_add3_u32 v186, v186, v194, s69
	v_add3_u32 v187, v187, v195, s69
	v_add3_u32 v188, v188, v196, s69
	v_add3_u32 v189, v189, v197, s69
	v_add3_u32 v190, v190, v198, s69
	v_add3_u32 v191, v191, v199, s69
	v_and_b32_e32 v185, 0xffff0000, v185
	v_and_b32_e32 v187, 0xffff0000, v187
	v_and_b32_e32 v189, 0xffff0000, v189
	v_and_b32_e32 v191, 0xffff0000, v191
	v_or_b32_sdwa v200, v185, v184 dst_sel:DWORD dst_unused:UNUSED_PAD src0_sel:DWORD src1_sel:WORD_1
	v_or_b32_sdwa v201, v187, v186 dst_sel:DWORD dst_unused:UNUSED_PAD src0_sel:DWORD src1_sel:WORD_1
	v_or_b32_sdwa v202, v189, v188 dst_sel:DWORD dst_unused:UNUSED_PAD src0_sel:DWORD src1_sel:WORD_1
	v_or_b32_sdwa v203, v191, v190 dst_sel:DWORD dst_unused:UNUSED_PAD src0_sel:DWORD src1_sel:WORD_1
	s_nop 1
	v_permlane16_swap_b32_e32 v200, v202
	v_permlane16_swap_b32_e32 v201, v203
	global_store_dwordx4 v210, v[200:203], s[84:85]
	v_mul_f32_e32 v184, s86, v28
	v_mul_f32_e32 v185, s86, v29
	v_mul_f32_e32 v186, s86, v30
	v_mul_f32_e32 v187, s86, v31
	v_mul_f32_e32 v188, s86, v20
	v_mul_f32_e32 v189, s86, v21
	v_mul_f32_e32 v190, s86, v22
	v_mul_f32_e32 v191, s86, v23
	v_and_b32_sdwa v192, v184, v110 dst_sel:DWORD dst_unused:UNUSED_PAD src0_sel:WORD_1 src1_sel:DWORD
	v_and_b32_sdwa v193, v185, v110 dst_sel:DWORD dst_unused:UNUSED_PAD src0_sel:WORD_1 src1_sel:DWORD
	v_and_b32_sdwa v194, v186, v110 dst_sel:DWORD dst_unused:UNUSED_PAD src0_sel:WORD_1 src1_sel:DWORD
	v_and_b32_sdwa v195, v187, v110 dst_sel:DWORD dst_unused:UNUSED_PAD src0_sel:WORD_1 src1_sel:DWORD
	v_and_b32_sdwa v196, v188, v110 dst_sel:DWORD dst_unused:UNUSED_PAD src0_sel:WORD_1 src1_sel:DWORD
	v_and_b32_sdwa v197, v189, v110 dst_sel:DWORD dst_unused:UNUSED_PAD src0_sel:WORD_1 src1_sel:DWORD
	v_and_b32_sdwa v198, v190, v110 dst_sel:DWORD dst_unused:UNUSED_PAD src0_sel:WORD_1 src1_sel:DWORD
	v_and_b32_sdwa v199, v191, v110 dst_sel:DWORD dst_unused:UNUSED_PAD src0_sel:WORD_1 src1_sel:DWORD
	v_add3_u32 v184, v184, v192, s69
	v_add3_u32 v185, v185, v193, s69
	v_add3_u32 v186, v186, v194, s69
	v_add3_u32 v187, v187, v195, s69
	v_add3_u32 v188, v188, v196, s69
	v_add3_u32 v189, v189, v197, s69
	v_add3_u32 v190, v190, v198, s69
	v_add3_u32 v191, v191, v199, s69
	v_and_b32_e32 v185, 0xffff0000, v185
	v_and_b32_e32 v187, 0xffff0000, v187
	v_and_b32_e32 v189, 0xffff0000, v189
	v_and_b32_e32 v191, 0xffff0000, v191
	v_or_b32_sdwa v204, v185, v184 dst_sel:DWORD dst_unused:UNUSED_PAD src0_sel:DWORD src1_sel:WORD_1
	v_or_b32_sdwa v205, v187, v186 dst_sel:DWORD dst_unused:UNUSED_PAD src0_sel:DWORD src1_sel:WORD_1
	v_or_b32_sdwa v206, v189, v188 dst_sel:DWORD dst_unused:UNUSED_PAD src0_sel:DWORD src1_sel:WORD_1
	v_or_b32_sdwa v207, v191, v190 dst_sel:DWORD dst_unused:UNUSED_PAD src0_sel:DWORD src1_sel:WORD_1
	s_nop 1
	v_permlane16_swap_b32_e32 v204, v206
	v_permlane16_swap_b32_e32 v205, v207
	global_store_dwordx4 v210, v[204:207], s[84:85] offset:64
	v_mul_f32_e32 v184, s86, v8
	v_mul_f32_e32 v185, s86, v9
	v_mul_f32_e32 v186, s86, v10
	v_mul_f32_e32 v187, s86, v11
	v_mul_f32_e32 v188, s86, v0
	v_mul_f32_e32 v189, s86, v1
	v_mul_f32_e32 v190, s86, v2
	v_mul_f32_e32 v191, s86, v3
	v_and_b32_sdwa v192, v184, v110 dst_sel:DWORD dst_unused:UNUSED_PAD src0_sel:WORD_1 src1_sel:DWORD
	v_and_b32_sdwa v193, v185, v110 dst_sel:DWORD dst_unused:UNUSED_PAD src0_sel:WORD_1 src1_sel:DWORD
	v_and_b32_sdwa v194, v186, v110 dst_sel:DWORD dst_unused:UNUSED_PAD src0_sel:WORD_1 src1_sel:DWORD
	v_and_b32_sdwa v195, v187, v110 dst_sel:DWORD dst_unused:UNUSED_PAD src0_sel:WORD_1 src1_sel:DWORD
	v_and_b32_sdwa v196, v188, v110 dst_sel:DWORD dst_unused:UNUSED_PAD src0_sel:WORD_1 src1_sel:DWORD
	v_and_b32_sdwa v197, v189, v110 dst_sel:DWORD dst_unused:UNUSED_PAD src0_sel:WORD_1 src1_sel:DWORD
	v_and_b32_sdwa v198, v190, v110 dst_sel:DWORD dst_unused:UNUSED_PAD src0_sel:WORD_1 src1_sel:DWORD
	v_and_b32_sdwa v199, v191, v110 dst_sel:DWORD dst_unused:UNUSED_PAD src0_sel:WORD_1 src1_sel:DWORD
	v_add3_u32 v184, v184, v192, s69
	v_add3_u32 v185, v185, v193, s69
	v_add3_u32 v186, v186, v194, s69
	v_add3_u32 v187, v187, v195, s69
	v_add3_u32 v188, v188, v196, s69
	v_add3_u32 v189, v189, v197, s69
	v_add3_u32 v190, v190, v198, s69
	v_add3_u32 v191, v191, v199, s69
	v_and_b32_e32 v185, 0xffff0000, v185
	v_and_b32_e32 v187, 0xffff0000, v187
	v_and_b32_e32 v189, 0xffff0000, v189
	v_and_b32_e32 v191, 0xffff0000, v191
	v_or_b32_sdwa v200, v185, v184 dst_sel:DWORD dst_unused:UNUSED_PAD src0_sel:DWORD src1_sel:WORD_1
	v_or_b32_sdwa v201, v187, v186 dst_sel:DWORD dst_unused:UNUSED_PAD src0_sel:DWORD src1_sel:WORD_1
	v_or_b32_sdwa v202, v189, v188 dst_sel:DWORD dst_unused:UNUSED_PAD src0_sel:DWORD src1_sel:WORD_1
	v_or_b32_sdwa v203, v191, v190 dst_sel:DWORD dst_unused:UNUSED_PAD src0_sel:DWORD src1_sel:WORD_1
	s_nop 1
	v_permlane16_swap_b32_e32 v200, v202
	v_permlane16_swap_b32_e32 v201, v203
	global_store_dwordx4 v211, v[200:203], s[84:85]
	v_mul_f32_e32 v184, s86, v12
	v_mul_f32_e32 v185, s86, v13
	v_mul_f32_e32 v186, s86, v14
	v_mul_f32_e32 v187, s86, v15
	v_mul_f32_e32 v188, s86, v4
	v_mul_f32_e32 v189, s86, v5
	v_mul_f32_e32 v190, s86, v6
	v_mul_f32_e32 v191, s86, v7
	v_and_b32_sdwa v192, v184, v110 dst_sel:DWORD dst_unused:UNUSED_PAD src0_sel:WORD_1 src1_sel:DWORD
	v_and_b32_sdwa v193, v185, v110 dst_sel:DWORD dst_unused:UNUSED_PAD src0_sel:WORD_1 src1_sel:DWORD
	v_and_b32_sdwa v194, v186, v110 dst_sel:DWORD dst_unused:UNUSED_PAD src0_sel:WORD_1 src1_sel:DWORD
	v_and_b32_sdwa v195, v187, v110 dst_sel:DWORD dst_unused:UNUSED_PAD src0_sel:WORD_1 src1_sel:DWORD
	v_and_b32_sdwa v196, v188, v110 dst_sel:DWORD dst_unused:UNUSED_PAD src0_sel:WORD_1 src1_sel:DWORD
	v_and_b32_sdwa v197, v189, v110 dst_sel:DWORD dst_unused:UNUSED_PAD src0_sel:WORD_1 src1_sel:DWORD
	v_and_b32_sdwa v198, v190, v110 dst_sel:DWORD dst_unused:UNUSED_PAD src0_sel:WORD_1 src1_sel:DWORD
	v_and_b32_sdwa v199, v191, v110 dst_sel:DWORD dst_unused:UNUSED_PAD src0_sel:WORD_1 src1_sel:DWORD
	v_add3_u32 v184, v184, v192, s69
	v_add3_u32 v185, v185, v193, s69
	v_add3_u32 v186, v186, v194, s69
	v_add3_u32 v187, v187, v195, s69
	v_add3_u32 v188, v188, v196, s69
	v_add3_u32 v189, v189, v197, s69
	v_add3_u32 v190, v190, v198, s69
	v_add3_u32 v191, v191, v199, s69
	v_and_b32_e32 v185, 0xffff0000, v185
	v_and_b32_e32 v187, 0xffff0000, v187
	v_and_b32_e32 v189, 0xffff0000, v189
	v_and_b32_e32 v191, 0xffff0000, v191
	v_or_b32_sdwa v204, v185, v184 dst_sel:DWORD dst_unused:UNUSED_PAD src0_sel:DWORD src1_sel:WORD_1
	v_or_b32_sdwa v205, v187, v186 dst_sel:DWORD dst_unused:UNUSED_PAD src0_sel:DWORD src1_sel:WORD_1
	v_or_b32_sdwa v206, v189, v188 dst_sel:DWORD dst_unused:UNUSED_PAD src0_sel:DWORD src1_sel:WORD_1
	v_or_b32_sdwa v207, v191, v190 dst_sel:DWORD dst_unused:UNUSED_PAD src0_sel:DWORD src1_sel:WORD_1
	s_nop 1
	v_permlane16_swap_b32_e32 v204, v206
	v_permlane16_swap_b32_e32 v205, v207
	global_store_dwordx4 v211, v[204:207], s[84:85] offset:64
	s_branch .Lep1a_done

.LBB0_664:
	v_lshrrev_b32_e32 v84, 3, v168
	v_lshrrev_b32_e32 v85, 4, v168
	v_xor_b32_e32 v85, v85, v168
	v_and_b32_e32 v85, 7, v85
	v_lshlrev_b32_e32 v85, 4, v85
	v_lshl_or_b32 v72, v84, 11, v85
	v_add_u32_e32 v73, 0x10000, v72
	v_add_u32_e32 v66, 0x20000, v72
	v_add_u32_e32 v67, 0x30000, v72
	s_load_dwordx2 s[90:91], s[0:1], 0xf0
	s_load_dwordx2 s[92:93], s[0:1], 0xc8
	v_lshrrev_b32_e32 v85, 6, v168
	s_nop 1
	v_readfirstlane_b32 s97, v85
	s_nop 3
	s_lshl_b32 s96, s97, 10
	s_add_u32 s96, s96, 16
	s_add_u32 s94, s61, s60
	s_cmp_lt_i32 s94, s62
	s_cselect_b32 s95, 1, 0
	s_cmp_lg_u64 s[12:13], 0
	s_cselect_b32 s95, 0, s95
	s_cmp_ge_u32 s94, 0x80
	s_cselect_b32 s97, 1, 0
	s_mul_i32 s100, s97, 0x80
	s_sub_u32 s100, s94, s100
	s_lshr_b32 s101, s100, 3
	s_and_b32 s100, s100, 7
	s_lshl_b32 s97, s97, 3
	s_add_u32 s100, s100, s97
	s_add_u32 s100, s100, s3
	s_cmp_lg_u32 s100, s50
	s_cselect_b32 s95, 0, s95
	s_cmp_eq_u32 s95, 1
	s_cselect_b32 s101, s101, s48
	s_mov_b32 s83, s101
	s_waitcnt lgkmcnt(0)
	s_lshl_b32 s101, s101, 18
	s_add_u32 s98, s92, s101
	s_addc_u32 s99, s93, 0
	s_lshl_b32 s94, s48, 18
	s_add_u32 s92, s92, s94
	s_addc_u32 s93, s93, 0
	s_lshl_b32 s94, s50, 18
	s_add_u32 s90, s90, s94
	s_addc_u32 s91, s91, 0
	s_waitcnt vmcnt(0)
	s_barrier
	s_add_u32 m0, s96, 0x0
	s_nop 0
	global_load_lds_dwordx4 v72, s[90:91]
	s_add_u32 m0, s96, 0x1000
	s_nop 0
	global_load_lds_dwordx4 v73, s[90:91]
	s_add_u32 m0, s96, 0x2000
	s_nop 0
	global_load_lds_dwordx4 v66, s[90:91]
	s_add_u32 m0, s96, 0x3000
	s_nop 0
	global_load_lds_dwordx4 v67, s[90:91]
	s_add_u32 m0, s96, 0x8000
	s_nop 0
	global_load_lds_dwordx4 v72, s[92:93]
	s_add_u32 m0, s96, 0x9000
	s_nop 0
	global_load_lds_dwordx4 v73, s[92:93]
	s_add_u32 m0, s96, 0xa000
	s_nop 0
	global_load_lds_dwordx4 v66, s[92:93]
	s_add_u32 m0, s96, 0xb000
	s_nop 0
	global_load_lds_dwordx4 v67, s[92:93]
	s_add_u32 m0, s96, 0xc000
	s_nop 0
	global_load_lds_dwordx4 v72, s[98:99]
	s_add_u32 m0, s96, 0xd000
	s_nop 0
	global_load_lds_dwordx4 v73, s[98:99]
	s_add_u32 m0, s96, 0xe000
	s_nop 0
	global_load_lds_dwordx4 v66, s[98:99]
	s_add_u32 m0, s96, 0xf000
	s_nop 0
	global_load_lds_dwordx4 v67, s[98:99]
	s_add_u32 s90, s90, 0x80
	s_addc_u32 s91, s91, 0
	s_add_u32 s92, s92, 0x80
	s_addc_u32 s93, s93, 0
	s_add_u32 s98, s98, 0x80
	s_addc_u32 s99, s99, 0
	s_and_b64 vcc, exec, s[6:7]
	s_cbranch_vccnz .Lgp9_nosleep
	s_sleep 8
.Lgp9_nosleep:
	v_mov_b32_e32 v0, 0
	v_mov_b32_e32 v1, v0
	v_mov_b32_e32 v2, v0
	v_mov_b32_e32 v3, v0
	v_mov_b32_e32 v4, v0
	v_mov_b32_e32 v5, v0
	v_mov_b32_e32 v6, v0
	v_mov_b32_e32 v7, v0
	v_mov_b32_e32 v8, v0
	v_mov_b32_e32 v9, v0
	v_mov_b32_e32 v10, v0
	v_mov_b32_e32 v11, v0
	v_mov_b32_e32 v12, v0
	v_mov_b32_e32 v13, v0
	v_mov_b32_e32 v14, v0
	v_mov_b32_e32 v15, v0
	v_mov_b32_e32 v16, v0
	v_mov_b32_e32 v17, v0
	v_mov_b32_e32 v18, v0
	v_mov_b32_e32 v19, v0
	v_mov_b32_e32 v20, v0
	v_mov_b32_e32 v21, v0
	v_mov_b32_e32 v22, v0
	v_mov_b32_e32 v23, v0
	v_mov_b32_e32 v24, v0
	v_mov_b32_e32 v25, v0
	v_mov_b32_e32 v26, v0
	v_mov_b32_e32 v27, v0
	v_mov_b32_e32 v28, v0
	v_mov_b32_e32 v29, v0
	v_mov_b32_e32 v30, v0
	v_mov_b32_e32 v31, v0
	v_mov_b32_e32 v32, v0
	v_mov_b32_e32 v33, v0
	v_mov_b32_e32 v34, v0
	v_mov_b32_e32 v35, v0
	v_mov_b32_e32 v36, v0
	v_mov_b32_e32 v37, v0
	v_mov_b32_e32 v38, v0
	v_mov_b32_e32 v39, v0
	v_mov_b32_e32 v40, v0
	v_mov_b32_e32 v41, v0
	v_mov_b32_e32 v42, v0
	v_mov_b32_e32 v43, v0
	v_mov_b32_e32 v44, v0
	v_mov_b32_e32 v45, v0
	v_mov_b32_e32 v46, v0
	v_mov_b32_e32 v47, v0
	v_mov_b32_e32 v48, v0
	v_mov_b32_e32 v49, v0
	v_mov_b32_e32 v50, v0
	v_mov_b32_e32 v51, v0
	v_mov_b32_e32 v52, v0
	v_mov_b32_e32 v53, v0
	v_mov_b32_e32 v54, v0
	v_mov_b32_e32 v55, v0
	v_mov_b32_e32 v56, v0
	v_mov_b32_e32 v57, v0
	v_mov_b32_e32 v58, v0
	v_mov_b32_e32 v59, v0
	v_mov_b32_e32 v60, v0
	v_mov_b32_e32 v61, v0
	v_mov_b32_e32 v62, v0
	v_mov_b32_e32 v63, v0
	v_mov_b32_e32 v116, v0
	v_mov_b32_e32 v117, v0
	v_mov_b32_e32 v118, v0
	v_mov_b32_e32 v119, v0
	v_mov_b32_e32 v120, v0
	v_mov_b32_e32 v121, v0
	v_mov_b32_e32 v122, v0
	v_mov_b32_e32 v123, v0
	v_mov_b32_e32 v124, v0
	v_mov_b32_e32 v125, v0
	v_mov_b32_e32 v126, v0
	v_mov_b32_e32 v127, v0
	v_mov_b32_e32 v128, v0
	v_mov_b32_e32 v129, v0
	v_mov_b32_e32 v130, v0
	v_mov_b32_e32 v131, v0
	v_mov_b32_e32 v132, v0
	v_mov_b32_e32 v133, v0
	v_mov_b32_e32 v134, v0
	v_mov_b32_e32 v135, v0
	v_mov_b32_e32 v136, v0
	v_mov_b32_e32 v137, v0
	v_mov_b32_e32 v138, v0
	v_mov_b32_e32 v139, v0
	v_mov_b32_e32 v140, v0
	v_mov_b32_e32 v141, v0
	v_mov_b32_e32 v142, v0
	v_mov_b32_e32 v143, v0
	v_mov_b32_e32 v148, v0
	v_mov_b32_e32 v149, v0
	v_mov_b32_e32 v150, v0
	v_mov_b32_e32 v151, v0
	v_mov_b32_e32 v152, v0
	v_mov_b32_e32 v153, v0
	v_mov_b32_e32 v154, v0
	v_mov_b32_e32 v155, v0
	v_mov_b32_e32 v156, v0
	v_mov_b32_e32 v157, v0
	v_mov_b32_e32 v158, v0
	v_mov_b32_e32 v159, v0
	v_mov_b32_e32 v160, v0
	v_mov_b32_e32 v161, v0
	v_mov_b32_e32 v162, v0
	v_mov_b32_e32 v163, v0
	v_mov_b32_e32 v172, v0
	v_mov_b32_e32 v173, v0
	v_mov_b32_e32 v174, v0
	v_mov_b32_e32 v175, v0
	v_mov_b32_e32 v176, v0
	v_mov_b32_e32 v177, v0
	v_mov_b32_e32 v178, v0
	v_mov_b32_e32 v179, v0
	v_mov_b32_e32 v180, v0
	v_mov_b32_e32 v181, v0
	v_mov_b32_e32 v182, v0
	v_mov_b32_e32 v183, v0
	v_mov_b32_e32 v184, v0
	v_mov_b32_e32 v185, v0
	v_mov_b32_e32 v186, v0
	v_mov_b32_e32 v187, v0
	v_mov_b32_e32 v188, v0
	v_mov_b32_e32 v189, v0
	v_mov_b32_e32 v190, v0
	v_mov_b32_e32 v191, v0
	s_mov_b32 s94, 0
.Lgp9_loop:
	s_waitcnt vmcnt(0) lgkmcnt(0)
	s_barrier
	s_add_u32 m0, s96, 0x4000
	s_nop 0
	global_load_lds_dwordx4 v72, s[90:91]
	s_add_u32 m0, s96, 0x5000
	s_nop 0
	global_load_lds_dwordx4 v73, s[90:91]
	s_add_u32 m0, s96, 0x6000
	s_nop 0
	global_load_lds_dwordx4 v66, s[90:91]
	s_add_u32 m0, s96, 0x7000
	s_nop 0
	global_load_lds_dwordx4 v67, s[90:91]
	s_add_u32 s90, s90, 0x80
	s_addc_u32 s91, s91, 0
	ds_read_b128 v[232:235], v87 offset:32768
	ds_read_b128 v[236:239], v87 offset:34816
	ds_read_b128 v[240:243], v87 offset:36864
	ds_read_b128 v[244:247], v87 offset:38912
	ds_read_b128 v[100:103], v87 offset:49152
	ds_read_b128 v[104:107], v87 offset:51200
	ds_read_b128 v[68:71], v87 offset:53248
	ds_read_b128 v[80:83], v87 offset:55296
	ds_read_b128 v[248:251], v89 offset:32768
	ds_read_b128 v[252:255], v89 offset:34816
	ds_read_b128 v[92:95], v89 offset:36864
	ds_read_b128 v[96:99], v89 offset:38912
	ds_read_b128 v[200:203], v89 offset:49152
	ds_read_b128 v[164:167], v89 offset:51200
	ds_read_b128 v[112:115], v89 offset:53248
	ds_read_b128 v[76:79], v89 offset:55296
	ds_read_b128 v[192:195], v86
	ds_read_b128 v[204:207], v86 offset:2048
	ds_read_b128 v[208:211], v86 offset:4096
	ds_read_b128 v[212:215], v86 offset:6144
	s_waitcnt lgkmcnt(0)
	s_barrier
	ds_read_b128 v[216:219], v88
	ds_read_b128 v[220:223], v88 offset:2048
	ds_read_b128 v[224:227], v88 offset:4096
	ds_read_b128 v[228:231], v88 offset:6144
	s_add_u32 m0, s96, 0x8000
	v_mfma_f32_16x16x32_bf16 v[0:3], v[232:235], v[192:195], v[0:3]
	global_load_lds_dwordx4 v72, s[92:93]
	v_mfma_f32_16x16x32_bf16 v[116:119], v[100:103], v[192:195], v[116:119]
	s_add_u32 m0, s96, 0x9000
	v_mfma_f32_16x16x32_bf16 v[4:7], v[236:239], v[192:195], v[4:7]
	global_load_lds_dwordx4 v73, s[92:93]
	v_mfma_f32_16x16x32_bf16 v[120:123], v[104:107], v[192:195], v[120:123]
	s_add_u32 m0, s96, 0xa000
	v_mfma_f32_16x16x32_bf16 v[8:11], v[240:243], v[192:195], v[8:11]
	global_load_lds_dwordx4 v66, s[92:93]
	v_mfma_f32_16x16x32_bf16 v[124:127], v[68:71], v[192:195], v[124:127]
	s_add_u32 m0, s96, 0xb000
	v_mfma_f32_16x16x32_bf16 v[12:15], v[244:247], v[192:195], v[12:15]
	global_load_lds_dwordx4 v67, s[92:93]
	v_mfma_f32_16x16x32_bf16 v[128:131], v[80:83], v[192:195], v[128:131]
	s_add_u32 m0, s96, 0xc000
	v_mfma_f32_16x16x32_bf16 v[16:19], v[232:235], v[204:207], v[16:19]
	global_load_lds_dwordx4 v72, s[98:99]
	v_mfma_f32_16x16x32_bf16 v[132:135], v[100:103], v[204:207], v[132:135]
	s_add_u32 m0, s96, 0xd000
	v_mfma_f32_16x16x32_bf16 v[20:23], v[236:239], v[204:207], v[20:23]
	global_load_lds_dwordx4 v73, s[98:99]
	v_mfma_f32_16x16x32_bf16 v[136:139], v[104:107], v[204:207], v[136:139]
	s_add_u32 m0, s96, 0xe000
	v_mfma_f32_16x16x32_bf16 v[24:27], v[240:243], v[204:207], v[24:27]
	global_load_lds_dwordx4 v66, s[98:99]
	v_mfma_f32_16x16x32_bf16 v[140:143], v[68:71], v[204:207], v[140:143]
	s_add_u32 m0, s96, 0xf000
	v_mfma_f32_16x16x32_bf16 v[28:31], v[244:247], v[204:207], v[28:31]
	global_load_lds_dwordx4 v67, s[98:99]
	s_add_u32 s92, s92, 0x80
	s_addc_u32 s93, s93, 0
	s_add_u32 s98, s98, 0x80
	s_addc_u32 s99, s99, 0
	v_mfma_f32_16x16x32_bf16 v[148:151], v[80:83], v[204:207], v[148:151]
	v_mfma_f32_16x16x32_bf16 v[32:35], v[232:235], v[208:211], v[32:35]
	v_mfma_f32_16x16x32_bf16 v[152:155], v[100:103], v[208:211], v[152:155]
	v_mfma_f32_16x16x32_bf16 v[36:39], v[236:239], v[208:211], v[36:39]
	v_mfma_f32_16x16x32_bf16 v[156:159], v[104:107], v[208:211], v[156:159]
	v_mfma_f32_16x16x32_bf16 v[40:43], v[240:243], v[208:211], v[40:43]
	v_mfma_f32_16x16x32_bf16 v[160:163], v[68:71], v[208:211], v[160:163]
	v_mfma_f32_16x16x32_bf16 v[44:47], v[244:247], v[208:211], v[44:47]
	v_mfma_f32_16x16x32_bf16 v[172:175], v[80:83], v[208:211], v[172:175]
	v_mfma_f32_16x16x32_bf16 v[48:51], v[232:235], v[212:215], v[48:51]
	v_mfma_f32_16x16x32_bf16 v[176:179], v[100:103], v[212:215], v[176:179]
	v_mfma_f32_16x16x32_bf16 v[52:55], v[236:239], v[212:215], v[52:55]
	v_mfma_f32_16x16x32_bf16 v[180:183], v[104:107], v[212:215], v[180:183]
	v_mfma_f32_16x16x32_bf16 v[56:59], v[240:243], v[212:215], v[56:59]
	v_mfma_f32_16x16x32_bf16 v[184:187], v[68:71], v[212:215], v[184:187]
	v_mfma_f32_16x16x32_bf16 v[60:63], v[244:247], v[212:215], v[60:63]
	v_mfma_f32_16x16x32_bf16 v[188:191], v[80:83], v[212:215], v[188:191]
	s_waitcnt lgkmcnt(0)
	v_mfma_f32_16x16x32_bf16 v[0:3], v[248:251], v[216:219], v[0:3]
	v_mfma_f32_16x16x32_bf16 v[116:119], v[200:203], v[216:219], v[116:119]
	v_mfma_f32_16x16x32_bf16 v[4:7], v[252:255], v[216:219], v[4:7]
	v_mfma_f32_16x16x32_bf16 v[120:123], v[164:167], v[216:219], v[120:123]
	v_mfma_f32_16x16x32_bf16 v[8:11], v[92:95], v[216:219], v[8:11]
	v_mfma_f32_16x16x32_bf16 v[124:127], v[112:115], v[216:219], v[124:127]
	v_mfma_f32_16x16x32_bf16 v[12:15], v[96:99], v[216:219], v[12:15]
	v_mfma_f32_16x16x32_bf16 v[128:131], v[76:79], v[216:219], v[128:131]
	v_mfma_f32_16x16x32_bf16 v[16:19], v[248:251], v[220:223], v[16:19]
	v_mfma_f32_16x16x32_bf16 v[132:135], v[200:203], v[220:223], v[132:135]
	v_mfma_f32_16x16x32_bf16 v[20:23], v[252:255], v[220:223], v[20:23]
	v_mfma_f32_16x16x32_bf16 v[136:139], v[164:167], v[220:223], v[136:139]
	v_mfma_f32_16x16x32_bf16 v[24:27], v[92:95], v[220:223], v[24:27]
	v_mfma_f32_16x16x32_bf16 v[140:143], v[112:115], v[220:223], v[140:143]
	v_mfma_f32_16x16x32_bf16 v[28:31], v[96:99], v[220:223], v[28:31]
	v_mfma_f32_16x16x32_bf16 v[148:151], v[76:79], v[220:223], v[148:151]
	v_mfma_f32_16x16x32_bf16 v[32:35], v[248:251], v[224:227], v[32:35]
	v_mfma_f32_16x16x32_bf16 v[152:155], v[200:203], v[224:227], v[152:155]
	v_mfma_f32_16x16x32_bf16 v[36:39], v[252:255], v[224:227], v[36:39]
	v_mfma_f32_16x16x32_bf16 v[156:159], v[164:167], v[224:227], v[156:159]
	v_mfma_f32_16x16x32_bf16 v[40:43], v[92:95], v[224:227], v[40:43]
	v_mfma_f32_16x16x32_bf16 v[160:163], v[112:115], v[224:227], v[160:163]
	v_mfma_f32_16x16x32_bf16 v[44:47], v[96:99], v[224:227], v[44:47]
	v_mfma_f32_16x16x32_bf16 v[172:175], v[76:79], v[224:227], v[172:175]
	v_mfma_f32_16x16x32_bf16 v[48:51], v[248:251], v[228:231], v[48:51]
	v_mfma_f32_16x16x32_bf16 v[176:179], v[200:203], v[228:231], v[176:179]
	v_mfma_f32_16x16x32_bf16 v[52:55], v[252:255], v[228:231], v[52:55]
	v_mfma_f32_16x16x32_bf16 v[180:183], v[164:167], v[228:231], v[180:183]
	v_mfma_f32_16x16x32_bf16 v[56:59], v[92:95], v[228:231], v[56:59]
	v_mfma_f32_16x16x32_bf16 v[184:187], v[112:115], v[228:231], v[184:187]
	v_mfma_f32_16x16x32_bf16 v[60:63], v[96:99], v[228:231], v[60:63]
	v_mfma_f32_16x16x32_bf16 v[188:191], v[76:79], v[228:231], v[188:191]
	s_waitcnt vmcnt(0) lgkmcnt(0)
	s_barrier
	s_cmp_eq_u32 s94, 7
	s_cbranch_scc1 .Lgp9_noS
	s_add_u32 m0, s96, 0x0
	s_nop 0
	global_load_lds_dwordx4 v72, s[90:91]
	s_add_u32 m0, s96, 0x1000
	s_nop 0
	global_load_lds_dwordx4 v73, s[90:91]
	s_add_u32 m0, s96, 0x2000
	s_nop 0
	global_load_lds_dwordx4 v66, s[90:91]
	s_add_u32 m0, s96, 0x3000
	s_nop 0
	global_load_lds_dwordx4 v67, s[90:91]
	s_add_u32 s90, s90, 0x80
	s_addc_u32 s91, s91, 0
.Lgp9_noS:
	ds_read_b128 v[232:235], v87 offset:32768
	ds_read_b128 v[236:239], v87 offset:34816
	ds_read_b128 v[240:243], v87 offset:36864
	ds_read_b128 v[244:247], v87 offset:38912
	ds_read_b128 v[100:103], v87 offset:49152
	ds_read_b128 v[104:107], v87 offset:51200
	ds_read_b128 v[68:71], v87 offset:53248
	ds_read_b128 v[80:83], v87 offset:55296
	ds_read_b128 v[248:251], v89 offset:32768
	ds_read_b128 v[252:255], v89 offset:34816
	ds_read_b128 v[92:95], v89 offset:36864
	ds_read_b128 v[96:99], v89 offset:38912
	ds_read_b128 v[200:203], v89 offset:49152
	ds_read_b128 v[164:167], v89 offset:51200
	ds_read_b128 v[112:115], v89 offset:53248
	ds_read_b128 v[76:79], v89 offset:55296
	ds_read_b128 v[192:195], v86 offset:16384
	ds_read_b128 v[204:207], v86 offset:18432
	ds_read_b128 v[208:211], v86 offset:20480
	ds_read_b128 v[212:215], v86 offset:22528
	s_waitcnt lgkmcnt(0)
	s_barrier
	ds_read_b128 v[216:219], v88 offset:16384
	ds_read_b128 v[220:223], v88 offset:18432
	ds_read_b128 v[224:227], v88 offset:20480
	ds_read_b128 v[228:231], v88 offset:22528
	s_cmp_eq_u32 s94, 7
	s_cbranch_scc1 .Lgp9_last
	s_add_u32 m0, s96, 0x8000
	v_mfma_f32_16x16x32_bf16 v[0:3], v[232:235], v[192:195], v[0:3]
	global_load_lds_dwordx4 v72, s[92:93]
	v_mfma_f32_16x16x32_bf16 v[116:119], v[100:103], v[192:195], v[116:119]
	s_add_u32 m0, s96, 0x9000
	v_mfma_f32_16x16x32_bf16 v[4:7], v[236:239], v[192:195], v[4:7]
	global_load_lds_dwordx4 v73, s[92:93]
	v_mfma_f32_16x16x32_bf16 v[120:123], v[104:107], v[192:195], v[120:123]
	s_add_u32 m0, s96, 0xa000
	v_mfma_f32_16x16x32_bf16 v[8:11], v[240:243], v[192:195], v[8:11]
	global_load_lds_dwordx4 v66, s[92:93]
	v_mfma_f32_16x16x32_bf16 v[124:127], v[68:71], v[192:195], v[124:127]
	s_add_u32 m0, s96, 0xb000
	v_mfma_f32_16x16x32_bf16 v[12:15], v[244:247], v[192:195], v[12:15]
	global_load_lds_dwordx4 v67, s[92:93]
	v_mfma_f32_16x16x32_bf16 v[128:131], v[80:83], v[192:195], v[128:131]
	s_add_u32 m0, s96, 0xc000
	v_mfma_f32_16x16x32_bf16 v[16:19], v[232:235], v[204:207], v[16:19]
	global_load_lds_dwordx4 v72, s[98:99]
	v_mfma_f32_16x16x32_bf16 v[132:135], v[100:103], v[204:207], v[132:135]
	s_add_u32 m0, s96, 0xd000
	v_mfma_f32_16x16x32_bf16 v[20:23], v[236:239], v[204:207], v[20:23]
	global_load_lds_dwordx4 v73, s[98:99]
	v_mfma_f32_16x16x32_bf16 v[136:139], v[104:107], v[204:207], v[136:139]
	s_add_u32 m0, s96, 0xe000
	v_mfma_f32_16x16x32_bf16 v[24:27], v[240:243], v[204:207], v[24:27]
	global_load_lds_dwordx4 v66, s[98:99]
	v_mfma_f32_16x16x32_bf16 v[140:143], v[68:71], v[204:207], v[140:143]
	s_add_u32 m0, s96, 0xf000
	v_mfma_f32_16x16x32_bf16 v[28:31], v[244:247], v[204:207], v[28:31]
	global_load_lds_dwordx4 v67, s[98:99]
	s_add_u32 s92, s92, 0x80
	s_addc_u32 s93, s93, 0
	s_add_u32 s98, s98, 0x80
	s_addc_u32 s99, s99, 0
	v_mfma_f32_16x16x32_bf16 v[148:151], v[80:83], v[204:207], v[148:151]
	v_mfma_f32_16x16x32_bf16 v[32:35], v[232:235], v[208:211], v[32:35]
	v_mfma_f32_16x16x32_bf16 v[152:155], v[100:103], v[208:211], v[152:155]
	v_mfma_f32_16x16x32_bf16 v[36:39], v[236:239], v[208:211], v[36:39]
	v_mfma_f32_16x16x32_bf16 v[156:159], v[104:107], v[208:211], v[156:159]
	v_mfma_f32_16x16x32_bf16 v[40:43], v[240:243], v[208:211], v[40:43]
	v_mfma_f32_16x16x32_bf16 v[160:163], v[68:71], v[208:211], v[160:163]
	v_mfma_f32_16x16x32_bf16 v[44:47], v[244:247], v[208:211], v[44:47]
	v_mfma_f32_16x16x32_bf16 v[172:175], v[80:83], v[208:211], v[172:175]
	v_mfma_f32_16x16x32_bf16 v[48:51], v[232:235], v[212:215], v[48:51]
	v_mfma_f32_16x16x32_bf16 v[176:179], v[100:103], v[212:215], v[176:179]
	v_mfma_f32_16x16x32_bf16 v[52:55], v[236:239], v[212:215], v[52:55]
	v_mfma_f32_16x16x32_bf16 v[180:183], v[104:107], v[212:215], v[180:183]
	v_mfma_f32_16x16x32_bf16 v[56:59], v[240:243], v[212:215], v[56:59]
	v_mfma_f32_16x16x32_bf16 v[184:187], v[68:71], v[212:215], v[184:187]
	v_mfma_f32_16x16x32_bf16 v[60:63], v[244:247], v[212:215], v[60:63]
	v_mfma_f32_16x16x32_bf16 v[188:191], v[80:83], v[212:215], v[188:191]
	s_waitcnt lgkmcnt(0)
	v_mfma_f32_16x16x32_bf16 v[0:3], v[248:251], v[216:219], v[0:3]
	v_mfma_f32_16x16x32_bf16 v[116:119], v[200:203], v[216:219], v[116:119]
	v_mfma_f32_16x16x32_bf16 v[4:7], v[252:255], v[216:219], v[4:7]
	v_mfma_f32_16x16x32_bf16 v[120:123], v[164:167], v[216:219], v[120:123]
	v_mfma_f32_16x16x32_bf16 v[8:11], v[92:95], v[216:219], v[8:11]
	v_mfma_f32_16x16x32_bf16 v[124:127], v[112:115], v[216:219], v[124:127]
	v_mfma_f32_16x16x32_bf16 v[12:15], v[96:99], v[216:219], v[12:15]
	v_mfma_f32_16x16x32_bf16 v[128:131], v[76:79], v[216:219], v[128:131]
	v_mfma_f32_16x16x32_bf16 v[16:19], v[248:251], v[220:223], v[16:19]
	v_mfma_f32_16x16x32_bf16 v[132:135], v[200:203], v[220:223], v[132:135]
	v_mfma_f32_16x16x32_bf16 v[20:23], v[252:255], v[220:223], v[20:23]
	v_mfma_f32_16x16x32_bf16 v[136:139], v[164:167], v[220:223], v[136:139]
	v_mfma_f32_16x16x32_bf16 v[24:27], v[92:95], v[220:223], v[24:27]
	v_mfma_f32_16x16x32_bf16 v[140:143], v[112:115], v[220:223], v[140:143]
	v_mfma_f32_16x16x32_bf16 v[28:31], v[96:99], v[220:223], v[28:31]
	v_mfma_f32_16x16x32_bf16 v[148:151], v[76:79], v[220:223], v[148:151]
	v_mfma_f32_16x16x32_bf16 v[32:35], v[248:251], v[224:227], v[32:35]
	v_mfma_f32_16x16x32_bf16 v[152:155], v[200:203], v[224:227], v[152:155]
	v_mfma_f32_16x16x32_bf16 v[36:39], v[252:255], v[224:227], v[36:39]
	v_mfma_f32_16x16x32_bf16 v[156:159], v[164:167], v[224:227], v[156:159]
	v_mfma_f32_16x16x32_bf16 v[40:43], v[92:95], v[224:227], v[40:43]
	v_mfma_f32_16x16x32_bf16 v[160:163], v[112:115], v[224:227], v[160:163]
	v_mfma_f32_16x16x32_bf16 v[44:47], v[96:99], v[224:227], v[44:47]
	v_mfma_f32_16x16x32_bf16 v[172:175], v[76:79], v[224:227], v[172:175]
	v_mfma_f32_16x16x32_bf16 v[48:51], v[248:251], v[228:231], v[48:51]
	v_mfma_f32_16x16x32_bf16 v[176:179], v[200:203], v[228:231], v[176:179]
	v_mfma_f32_16x16x32_bf16 v[52:55], v[252:255], v[228:231], v[52:55]
	v_mfma_f32_16x16x32_bf16 v[180:183], v[164:167], v[228:231], v[180:183]
	v_mfma_f32_16x16x32_bf16 v[56:59], v[92:95], v[228:231], v[56:59]
	v_mfma_f32_16x16x32_bf16 v[184:187], v[112:115], v[228:231], v[184:187]
	v_mfma_f32_16x16x32_bf16 v[60:63], v[96:99], v[228:231], v[60:63]
	v_mfma_f32_16x16x32_bf16 v[188:191], v[76:79], v[228:231], v[188:191]
	s_add_u32 s94, s94, 1
	s_branch .Lgp9_loop
.Lgp9_last:
	v_mfma_f32_16x16x32_bf16 v[0:3], v[232:235], v[192:195], v[0:3]
	v_mfma_f32_16x16x32_bf16 v[116:119], v[100:103], v[192:195], v[116:119]
	v_mfma_f32_16x16x32_bf16 v[4:7], v[236:239], v[192:195], v[4:7]
	v_mfma_f32_16x16x32_bf16 v[120:123], v[104:107], v[192:195], v[120:123]
	v_mfma_f32_16x16x32_bf16 v[8:11], v[240:243], v[192:195], v[8:11]
	v_mfma_f32_16x16x32_bf16 v[124:127], v[68:71], v[192:195], v[124:127]
	v_mfma_f32_16x16x32_bf16 v[12:15], v[244:247], v[192:195], v[12:15]
	v_mfma_f32_16x16x32_bf16 v[128:131], v[80:83], v[192:195], v[128:131]
	v_mfma_f32_16x16x32_bf16 v[16:19], v[232:235], v[204:207], v[16:19]
	v_mfma_f32_16x16x32_bf16 v[132:135], v[100:103], v[204:207], v[132:135]
	v_mfma_f32_16x16x32_bf16 v[20:23], v[236:239], v[204:207], v[20:23]
	v_mfma_f32_16x16x32_bf16 v[136:139], v[104:107], v[204:207], v[136:139]
	v_mfma_f32_16x16x32_bf16 v[24:27], v[240:243], v[204:207], v[24:27]
	v_mfma_f32_16x16x32_bf16 v[140:143], v[68:71], v[204:207], v[140:143]
	v_mfma_f32_16x16x32_bf16 v[28:31], v[244:247], v[204:207], v[28:31]
	v_mfma_f32_16x16x32_bf16 v[148:151], v[80:83], v[204:207], v[148:151]
	v_mfma_f32_16x16x32_bf16 v[32:35], v[232:235], v[208:211], v[32:35]
	v_mfma_f32_16x16x32_bf16 v[152:155], v[100:103], v[208:211], v[152:155]
	v_mfma_f32_16x16x32_bf16 v[36:39], v[236:239], v[208:211], v[36:39]
	v_mfma_f32_16x16x32_bf16 v[156:159], v[104:107], v[208:211], v[156:159]
	v_mfma_f32_16x16x32_bf16 v[40:43], v[240:243], v[208:211], v[40:43]
	v_mfma_f32_16x16x32_bf16 v[160:163], v[68:71], v[208:211], v[160:163]
	v_mfma_f32_16x16x32_bf16 v[44:47], v[244:247], v[208:211], v[44:47]
	v_mfma_f32_16x16x32_bf16 v[172:175], v[80:83], v[208:211], v[172:175]
	v_mfma_f32_16x16x32_bf16 v[48:51], v[232:235], v[212:215], v[48:51]
	v_mfma_f32_16x16x32_bf16 v[176:179], v[100:103], v[212:215], v[176:179]
	v_mfma_f32_16x16x32_bf16 v[52:55], v[236:239], v[212:215], v[52:55]
	v_mfma_f32_16x16x32_bf16 v[180:183], v[104:107], v[212:215], v[180:183]
	v_mfma_f32_16x16x32_bf16 v[56:59], v[240:243], v[212:215], v[56:59]
	v_mfma_f32_16x16x32_bf16 v[184:187], v[68:71], v[212:215], v[184:187]
	v_mfma_f32_16x16x32_bf16 v[60:63], v[244:247], v[212:215], v[60:63]
	v_mfma_f32_16x16x32_bf16 v[188:191], v[80:83], v[212:215], v[188:191]
	s_waitcnt lgkmcnt(0)
	v_mfma_f32_16x16x32_bf16 v[0:3], v[248:251], v[216:219], v[0:3]
	v_mfma_f32_16x16x32_bf16 v[116:119], v[200:203], v[216:219], v[116:119]
	v_mfma_f32_16x16x32_bf16 v[4:7], v[252:255], v[216:219], v[4:7]
	v_mfma_f32_16x16x32_bf16 v[120:123], v[164:167], v[216:219], v[120:123]
	v_mfma_f32_16x16x32_bf16 v[8:11], v[92:95], v[216:219], v[8:11]
	v_mfma_f32_16x16x32_bf16 v[124:127], v[112:115], v[216:219], v[124:127]
	v_mfma_f32_16x16x32_bf16 v[12:15], v[96:99], v[216:219], v[12:15]
	v_mfma_f32_16x16x32_bf16 v[128:131], v[76:79], v[216:219], v[128:131]
	v_mfma_f32_16x16x32_bf16 v[16:19], v[248:251], v[220:223], v[16:19]
	v_mfma_f32_16x16x32_bf16 v[132:135], v[200:203], v[220:223], v[132:135]
	v_mfma_f32_16x16x32_bf16 v[20:23], v[252:255], v[220:223], v[20:23]
	v_mfma_f32_16x16x32_bf16 v[136:139], v[164:167], v[220:223], v[136:139]
	v_mfma_f32_16x16x32_bf16 v[24:27], v[92:95], v[220:223], v[24:27]
	v_mfma_f32_16x16x32_bf16 v[140:143], v[112:115], v[220:223], v[140:143]
	v_mfma_f32_16x16x32_bf16 v[28:31], v[96:99], v[220:223], v[28:31]
	v_mfma_f32_16x16x32_bf16 v[148:151], v[76:79], v[220:223], v[148:151]
	v_mfma_f32_16x16x32_bf16 v[32:35], v[248:251], v[224:227], v[32:35]
	v_mfma_f32_16x16x32_bf16 v[152:155], v[200:203], v[224:227], v[152:155]
	v_mfma_f32_16x16x32_bf16 v[36:39], v[252:255], v[224:227], v[36:39]
	v_mfma_f32_16x16x32_bf16 v[156:159], v[164:167], v[224:227], v[156:159]
	v_mfma_f32_16x16x32_bf16 v[40:43], v[92:95], v[224:227], v[40:43]
	v_mfma_f32_16x16x32_bf16 v[160:163], v[112:115], v[224:227], v[160:163]
	v_mfma_f32_16x16x32_bf16 v[44:47], v[96:99], v[224:227], v[44:47]
	v_mfma_f32_16x16x32_bf16 v[172:175], v[76:79], v[224:227], v[172:175]
	v_mfma_f32_16x16x32_bf16 v[48:51], v[248:251], v[228:231], v[48:51]
	v_mfma_f32_16x16x32_bf16 v[176:179], v[200:203], v[228:231], v[176:179]
	v_mfma_f32_16x16x32_bf16 v[52:55], v[252:255], v[228:231], v[52:55]
	v_mfma_f32_16x16x32_bf16 v[180:183], v[164:167], v[228:231], v[180:183]
	v_mfma_f32_16x16x32_bf16 v[56:59], v[92:95], v[228:231], v[56:59]
	v_mfma_f32_16x16x32_bf16 v[184:187], v[112:115], v[228:231], v[184:187]
	v_mfma_f32_16x16x32_bf16 v[60:63], v[96:99], v[228:231], v[60:63]
	v_mfma_f32_16x16x32_bf16 v[188:191], v[76:79], v[228:231], v[188:191]
	s_nop 7
	s_nop 3
	s_load_dwordx2 s[84:85], s[0:1], 0xa0
	v_lshrrev_b32_e32 v232, 1, v168
	v_and_b32_e32 v232, 0x1c0, v232
	v_and_b32_e32 v233, 15, v168
	v_or_b32_e32 v232, v232, v233
	v_lshl_add_u32 v232, s50, 7, v232
	v_lshlrev_b32_e32 v232, 12, v232
	v_bfe_u32 v233, v168, 4, 2
	v_lshlrev_b32_e32 v229, 3, v233
	v_and_b32_e32 v233, 1, v233
	v_mul_u32_u24_e32 v233, 24, v233
	v_add3_u32 v232, v232, v233, v229
	v_bfe_u32 v233, v168, 6, 1
	s_lshl_b32 s87, s48, 8
	v_lshl_add_u32 v228, v233, 7, v232
	v_add_u32_e32 v228, s87, v228
	v_add_u32_e32 v229, 0x10000, v228
	v_add_u32_e32 v230, 0x20000, v228
	v_add_u32_e32 v231, 0x30000, v228
	s_waitcnt lgkmcnt(0)
	v_and_b32_sdwa v212, v0, v108 dst_sel:DWORD dst_unused:UNUSED_PAD src0_sel:WORD_1 src1_sel:DWORD
	v_and_b32_sdwa v213, v1, v108 dst_sel:DWORD dst_unused:UNUSED_PAD src0_sel:WORD_1 src1_sel:DWORD
	v_and_b32_sdwa v214, v2, v108 dst_sel:DWORD dst_unused:UNUSED_PAD src0_sel:WORD_1 src1_sel:DWORD
	v_and_b32_sdwa v215, v3, v108 dst_sel:DWORD dst_unused:UNUSED_PAD src0_sel:WORD_1 src1_sel:DWORD
	v_and_b32_sdwa v216, v4, v108 dst_sel:DWORD dst_unused:UNUSED_PAD src0_sel:WORD_1 src1_sel:DWORD
	v_and_b32_sdwa v217, v5, v108 dst_sel:DWORD dst_unused:UNUSED_PAD src0_sel:WORD_1 src1_sel:DWORD
	v_and_b32_sdwa v218, v6, v108 dst_sel:DWORD dst_unused:UNUSED_PAD src0_sel:WORD_1 src1_sel:DWORD
	v_and_b32_sdwa v219, v7, v108 dst_sel:DWORD dst_unused:UNUSED_PAD src0_sel:WORD_1 src1_sel:DWORD
	v_add3_u32 v204, v0, v212, s66
	v_add3_u32 v205, v1, v213, s66
	v_add3_u32 v206, v2, v214, s66
	v_add3_u32 v207, v3, v215, s66
	v_add3_u32 v208, v4, v216, s66
	v_add3_u32 v209, v5, v217, s66
	v_add3_u32 v210, v6, v218, s66
	v_add3_u32 v211, v7, v219, s66
	v_and_b32_e32 v205, 0xffff0000, v205
	v_and_b32_e32 v207, 0xffff0000, v207
	v_and_b32_e32 v209, 0xffff0000, v209
	v_and_b32_e32 v211, 0xffff0000, v211
	v_or_b32_sdwa v220, v205, v204 dst_sel:DWORD dst_unused:UNUSED_PAD src0_sel:DWORD src1_sel:WORD_1
	v_or_b32_sdwa v221, v207, v206 dst_sel:DWORD dst_unused:UNUSED_PAD src0_sel:DWORD src1_sel:WORD_1
	v_or_b32_sdwa v222, v209, v208 dst_sel:DWORD dst_unused:UNUSED_PAD src0_sel:DWORD src1_sel:WORD_1
	v_or_b32_sdwa v223, v211, v210 dst_sel:DWORD dst_unused:UNUSED_PAD src0_sel:DWORD src1_sel:WORD_1
	s_nop 1
	v_permlane16_swap_b32_e32 v220, v222
	v_permlane16_swap_b32_e32 v221, v223
	global_store_dwordx4 v228, v[220:223], s[84:85]
	v_and_b32_sdwa v212, v8, v108 dst_sel:DWORD dst_unused:UNUSED_PAD src0_sel:WORD_1 src1_sel:DWORD
	v_and_b32_sdwa v213, v9, v108 dst_sel:DWORD dst_unused:UNUSED_PAD src0_sel:WORD_1 src1_sel:DWORD
	v_and_b32_sdwa v214, v10, v108 dst_sel:DWORD dst_unused:UNUSED_PAD src0_sel:WORD_1 src1_sel:DWORD
	v_and_b32_sdwa v215, v11, v108 dst_sel:DWORD dst_unused:UNUSED_PAD src0_sel:WORD_1 src1_sel:DWORD
	v_and_b32_sdwa v216, v12, v108 dst_sel:DWORD dst_unused:UNUSED_PAD src0_sel:WORD_1 src1_sel:DWORD
	v_and_b32_sdwa v217, v13, v108 dst_sel:DWORD dst_unused:UNUSED_PAD src0_sel:WORD_1 src1_sel:DWORD
	v_and_b32_sdwa v218, v14, v108 dst_sel:DWORD dst_unused:UNUSED_PAD src0_sel:WORD_1 src1_sel:DWORD
	v_and_b32_sdwa v219, v15, v108 dst_sel:DWORD dst_unused:UNUSED_PAD src0_sel:WORD_1 src1_sel:DWORD
	v_add3_u32 v204, v8, v212, s66
	v_add3_u32 v205, v9, v213, s66
	v_add3_u32 v206, v10, v214, s66
	v_add3_u32 v207, v11, v215, s66
	v_add3_u32 v208, v12, v216, s66
	v_add3_u32 v209, v13, v217, s66
	v_add3_u32 v210, v14, v218, s66
	v_add3_u32 v211, v15, v219, s66
	v_and_b32_e32 v205, 0xffff0000, v205
	v_and_b32_e32 v207, 0xffff0000, v207
	v_and_b32_e32 v209, 0xffff0000, v209
	v_and_b32_e32 v211, 0xffff0000, v211
	v_or_b32_sdwa v224, v205, v204 dst_sel:DWORD dst_unused:UNUSED_PAD src0_sel:DWORD src1_sel:WORD_1
	v_or_b32_sdwa v225, v207, v206 dst_sel:DWORD dst_unused:UNUSED_PAD src0_sel:DWORD src1_sel:WORD_1
	v_or_b32_sdwa v226, v209, v208 dst_sel:DWORD dst_unused:UNUSED_PAD src0_sel:DWORD src1_sel:WORD_1
	v_or_b32_sdwa v227, v211, v210 dst_sel:DWORD dst_unused:UNUSED_PAD src0_sel:DWORD src1_sel:WORD_1
	s_nop 1
	v_permlane16_swap_b32_e32 v224, v226
	v_permlane16_swap_b32_e32 v225, v227
	global_store_dwordx4 v228, v[224:227], s[84:85] offset:64
	v_and_b32_sdwa v212, v16, v108 dst_sel:DWORD dst_unused:UNUSED_PAD src0_sel:WORD_1 src1_sel:DWORD
	v_and_b32_sdwa v213, v17, v108 dst_sel:DWORD dst_unused:UNUSED_PAD src0_sel:WORD_1 src1_sel:DWORD
	v_and_b32_sdwa v214, v18, v108 dst_sel:DWORD dst_unused:UNUSED_PAD src0_sel:WORD_1 src1_sel:DWORD
	v_and_b32_sdwa v215, v19, v108 dst_sel:DWORD dst_unused:UNUSED_PAD src0_sel:WORD_1 src1_sel:DWORD
	v_and_b32_sdwa v216, v20, v108 dst_sel:DWORD dst_unused:UNUSED_PAD src0_sel:WORD_1 src1_sel:DWORD
	v_and_b32_sdwa v217, v21, v108 dst_sel:DWORD dst_unused:UNUSED_PAD src0_sel:WORD_1 src1_sel:DWORD
	v_and_b32_sdwa v218, v22, v108 dst_sel:DWORD dst_unused:UNUSED_PAD src0_sel:WORD_1 src1_sel:DWORD
	v_and_b32_sdwa v219, v23, v108 dst_sel:DWORD dst_unused:UNUSED_PAD src0_sel:WORD_1 src1_sel:DWORD
	v_add3_u32 v204, v16, v212, s66
	v_add3_u32 v205, v17, v213, s66
	v_add3_u32 v206, v18, v214, s66
	v_add3_u32 v207, v19, v215, s66
	v_add3_u32 v208, v20, v216, s66
	v_add3_u32 v209, v21, v217, s66
	v_add3_u32 v210, v22, v218, s66
	v_add3_u32 v211, v23, v219, s66
	v_and_b32_e32 v205, 0xffff0000, v205
	v_and_b32_e32 v207, 0xffff0000, v207
	v_and_b32_e32 v209, 0xffff0000, v209
	v_and_b32_e32 v211, 0xffff0000, v211
	v_or_b32_sdwa v220, v205, v204 dst_sel:DWORD dst_unused:UNUSED_PAD src0_sel:DWORD src1_sel:WORD_1
	v_or_b32_sdwa v221, v207, v206 dst_sel:DWORD dst_unused:UNUSED_PAD src0_sel:DWORD src1_sel:WORD_1
	v_or_b32_sdwa v222, v209, v208 dst_sel:DWORD dst_unused:UNUSED_PAD src0_sel:DWORD src1_sel:WORD_1
	v_or_b32_sdwa v223, v211, v210 dst_sel:DWORD dst_unused:UNUSED_PAD src0_sel:DWORD src1_sel:WORD_1
	s_nop 1
	v_permlane16_swap_b32_e32 v220, v222
	v_permlane16_swap_b32_e32 v221, v223
	global_store_dwordx4 v229, v[220:223], s[84:85]
	v_and_b32_sdwa v212, v24, v108 dst_sel:DWORD dst_unused:UNUSED_PAD src0_sel:WORD_1 src1_sel:DWORD
	v_and_b32_sdwa v213, v25, v108 dst_sel:DWORD dst_unused:UNUSED_PAD src0_sel:WORD_1 src1_sel:DWORD
	v_and_b32_sdwa v214, v26, v108 dst_sel:DWORD dst_unused:UNUSED_PAD src0_sel:WORD_1 src1_sel:DWORD
	v_and_b32_sdwa v215, v27, v108 dst_sel:DWORD dst_unused:UNUSED_PAD src0_sel:WORD_1 src1_sel:DWORD
	v_and_b32_sdwa v216, v28, v108 dst_sel:DWORD dst_unused:UNUSED_PAD src0_sel:WORD_1 src1_sel:DWORD
	v_and_b32_sdwa v217, v29, v108 dst_sel:DWORD dst_unused:UNUSED_PAD src0_sel:WORD_1 src1_sel:DWORD
	v_and_b32_sdwa v218, v30, v108 dst_sel:DWORD dst_unused:UNUSED_PAD src0_sel:WORD_1 src1_sel:DWORD
	v_and_b32_sdwa v219, v31, v108 dst_sel:DWORD dst_unused:UNUSED_PAD src0_sel:WORD_1 src1_sel:DWORD
	v_add3_u32 v204, v24, v212, s66
	v_add3_u32 v205, v25, v213, s66
	v_add3_u32 v206, v26, v214, s66
	v_add3_u32 v207, v27, v215, s66
	v_add3_u32 v208, v28, v216, s66
	v_add3_u32 v209, v29, v217, s66
	v_add3_u32 v210, v30, v218, s66
	v_add3_u32 v211, v31, v219, s66
	v_and_b32_e32 v205, 0xffff0000, v205
	v_and_b32_e32 v207, 0xffff0000, v207
	v_and_b32_e32 v209, 0xffff0000, v209
	v_and_b32_e32 v211, 0xffff0000, v211
	v_or_b32_sdwa v224, v205, v204 dst_sel:DWORD dst_unused:UNUSED_PAD src0_sel:DWORD src1_sel:WORD_1
	v_or_b32_sdwa v225, v207, v206 dst_sel:DWORD dst_unused:UNUSED_PAD src0_sel:DWORD src1_sel:WORD_1
	v_or_b32_sdwa v226, v209, v208 dst_sel:DWORD dst_unused:UNUSED_PAD src0_sel:DWORD src1_sel:WORD_1
	v_or_b32_sdwa v227, v211, v210 dst_sel:DWORD dst_unused:UNUSED_PAD src0_sel:DWORD src1_sel:WORD_1
	s_nop 1
	v_permlane16_swap_b32_e32 v224, v226
	v_permlane16_swap_b32_e32 v225, v227
	global_store_dwordx4 v229, v[224:227], s[84:85] offset:64
	v_and_b32_sdwa v212, v32, v108 dst_sel:DWORD dst_unused:UNUSED_PAD src0_sel:WORD_1 src1_sel:DWORD
	v_and_b32_sdwa v213, v33, v108 dst_sel:DWORD dst_unused:UNUSED_PAD src0_sel:WORD_1 src1_sel:DWORD
	v_and_b32_sdwa v214, v34, v108 dst_sel:DWORD dst_unused:UNUSED_PAD src0_sel:WORD_1 src1_sel:DWORD
	v_and_b32_sdwa v215, v35, v108 dst_sel:DWORD dst_unused:UNUSED_PAD src0_sel:WORD_1 src1_sel:DWORD
	v_and_b32_sdwa v216, v36, v108 dst_sel:DWORD dst_unused:UNUSED_PAD src0_sel:WORD_1 src1_sel:DWORD
	v_and_b32_sdwa v217, v37, v108 dst_sel:DWORD dst_unused:UNUSED_PAD src0_sel:WORD_1 src1_sel:DWORD
	v_and_b32_sdwa v218, v38, v108 dst_sel:DWORD dst_unused:UNUSED_PAD src0_sel:WORD_1 src1_sel:DWORD
	v_and_b32_sdwa v219, v39, v108 dst_sel:DWORD dst_unused:UNUSED_PAD src0_sel:WORD_1 src1_sel:DWORD
	v_add3_u32 v204, v32, v212, s66
	v_add3_u32 v205, v33, v213, s66
	v_add3_u32 v206, v34, v214, s66
	v_add3_u32 v207, v35, v215, s66
	v_add3_u32 v208, v36, v216, s66
	v_add3_u32 v209, v37, v217, s66
	v_add3_u32 v210, v38, v218, s66
	v_add3_u32 v211, v39, v219, s66
	v_and_b32_e32 v205, 0xffff0000, v205
	v_and_b32_e32 v207, 0xffff0000, v207
	v_and_b32_e32 v209, 0xffff0000, v209
	v_and_b32_e32 v211, 0xffff0000, v211
	v_or_b32_sdwa v220, v205, v204 dst_sel:DWORD dst_unused:UNUSED_PAD src0_sel:DWORD src1_sel:WORD_1
	v_or_b32_sdwa v221, v207, v206 dst_sel:DWORD dst_unused:UNUSED_PAD src0_sel:DWORD src1_sel:WORD_1
	v_or_b32_sdwa v222, v209, v208 dst_sel:DWORD dst_unused:UNUSED_PAD src0_sel:DWORD src1_sel:WORD_1
	v_or_b32_sdwa v223, v211, v210 dst_sel:DWORD dst_unused:UNUSED_PAD src0_sel:DWORD src1_sel:WORD_1
	s_nop 1
	v_permlane16_swap_b32_e32 v220, v222
	v_permlane16_swap_b32_e32 v221, v223
	global_store_dwordx4 v230, v[220:223], s[84:85]
	v_and_b32_sdwa v212, v40, v108 dst_sel:DWORD dst_unused:UNUSED_PAD src0_sel:WORD_1 src1_sel:DWORD
	v_and_b32_sdwa v213, v41, v108 dst_sel:DWORD dst_unused:UNUSED_PAD src0_sel:WORD_1 src1_sel:DWORD
	v_and_b32_sdwa v214, v42, v108 dst_sel:DWORD dst_unused:UNUSED_PAD src0_sel:WORD_1 src1_sel:DWORD
	v_and_b32_sdwa v215, v43, v108 dst_sel:DWORD dst_unused:UNUSED_PAD src0_sel:WORD_1 src1_sel:DWORD
	v_and_b32_sdwa v216, v44, v108 dst_sel:DWORD dst_unused:UNUSED_PAD src0_sel:WORD_1 src1_sel:DWORD
	v_and_b32_sdwa v217, v45, v108 dst_sel:DWORD dst_unused:UNUSED_PAD src0_sel:WORD_1 src1_sel:DWORD
	v_and_b32_sdwa v218, v46, v108 dst_sel:DWORD dst_unused:UNUSED_PAD src0_sel:WORD_1 src1_sel:DWORD
	v_and_b32_sdwa v219, v47, v108 dst_sel:DWORD dst_unused:UNUSED_PAD src0_sel:WORD_1 src1_sel:DWORD
	v_add3_u32 v204, v40, v212, s66
	v_add3_u32 v205, v41, v213, s66
	v_add3_u32 v206, v42, v214, s66
	v_add3_u32 v207, v43, v215, s66
	v_add3_u32 v208, v44, v216, s66
	v_add3_u32 v209, v45, v217, s66
	v_add3_u32 v210, v46, v218, s66
	v_add3_u32 v211, v47, v219, s66
	v_and_b32_e32 v205, 0xffff0000, v205
	v_and_b32_e32 v207, 0xffff0000, v207
	v_and_b32_e32 v209, 0xffff0000, v209
	v_and_b32_e32 v211, 0xffff0000, v211
	v_or_b32_sdwa v224, v205, v204 dst_sel:DWORD dst_unused:UNUSED_PAD src0_sel:DWORD src1_sel:WORD_1
	v_or_b32_sdwa v225, v207, v206 dst_sel:DWORD dst_unused:UNUSED_PAD src0_sel:DWORD src1_sel:WORD_1
	v_or_b32_sdwa v226, v209, v208 dst_sel:DWORD dst_unused:UNUSED_PAD src0_sel:DWORD src1_sel:WORD_1
	v_or_b32_sdwa v227, v211, v210 dst_sel:DWORD dst_unused:UNUSED_PAD src0_sel:DWORD src1_sel:WORD_1
	s_nop 1
	v_permlane16_swap_b32_e32 v224, v226
	v_permlane16_swap_b32_e32 v225, v227
	global_store_dwordx4 v230, v[224:227], s[84:85] offset:64
	v_and_b32_sdwa v212, v48, v108 dst_sel:DWORD dst_unused:UNUSED_PAD src0_sel:WORD_1 src1_sel:DWORD
	v_and_b32_sdwa v213, v49, v108 dst_sel:DWORD dst_unused:UNUSED_PAD src0_sel:WORD_1 src1_sel:DWORD
	v_and_b32_sdwa v214, v50, v108 dst_sel:DWORD dst_unused:UNUSED_PAD src0_sel:WORD_1 src1_sel:DWORD
	v_and_b32_sdwa v215, v51, v108 dst_sel:DWORD dst_unused:UNUSED_PAD src0_sel:WORD_1 src1_sel:DWORD
	v_and_b32_sdwa v216, v52, v108 dst_sel:DWORD dst_unused:UNUSED_PAD src0_sel:WORD_1 src1_sel:DWORD
	v_and_b32_sdwa v217, v53, v108 dst_sel:DWORD dst_unused:UNUSED_PAD src0_sel:WORD_1 src1_sel:DWORD
	v_and_b32_sdwa v218, v54, v108 dst_sel:DWORD dst_unused:UNUSED_PAD src0_sel:WORD_1 src1_sel:DWORD
	v_and_b32_sdwa v219, v55, v108 dst_sel:DWORD dst_unused:UNUSED_PAD src0_sel:WORD_1 src1_sel:DWORD
	v_add3_u32 v204, v48, v212, s66
	v_add3_u32 v205, v49, v213, s66
	v_add3_u32 v206, v50, v214, s66
	v_add3_u32 v207, v51, v215, s66
	v_add3_u32 v208, v52, v216, s66
	v_add3_u32 v209, v53, v217, s66
	v_add3_u32 v210, v54, v218, s66
	v_add3_u32 v211, v55, v219, s66
	v_and_b32_e32 v205, 0xffff0000, v205
	v_and_b32_e32 v207, 0xffff0000, v207
	v_and_b32_e32 v209, 0xffff0000, v209
	v_and_b32_e32 v211, 0xffff0000, v211
	v_or_b32_sdwa v220, v205, v204 dst_sel:DWORD dst_unused:UNUSED_PAD src0_sel:DWORD src1_sel:WORD_1
	v_or_b32_sdwa v221, v207, v206 dst_sel:DWORD dst_unused:UNUSED_PAD src0_sel:DWORD src1_sel:WORD_1
	v_or_b32_sdwa v222, v209, v208 dst_sel:DWORD dst_unused:UNUSED_PAD src0_sel:DWORD src1_sel:WORD_1
	v_or_b32_sdwa v223, v211, v210 dst_sel:DWORD dst_unused:UNUSED_PAD src0_sel:DWORD src1_sel:WORD_1
	s_nop 1
	v_permlane16_swap_b32_e32 v220, v222
	v_permlane16_swap_b32_e32 v221, v223
	global_store_dwordx4 v231, v[220:223], s[84:85]
	v_and_b32_sdwa v212, v56, v108 dst_sel:DWORD dst_unused:UNUSED_PAD src0_sel:WORD_1 src1_sel:DWORD
	v_and_b32_sdwa v213, v57, v108 dst_sel:DWORD dst_unused:UNUSED_PAD src0_sel:WORD_1 src1_sel:DWORD
	v_and_b32_sdwa v214, v58, v108 dst_sel:DWORD dst_unused:UNUSED_PAD src0_sel:WORD_1 src1_sel:DWORD
	v_and_b32_sdwa v215, v59, v108 dst_sel:DWORD dst_unused:UNUSED_PAD src0_sel:WORD_1 src1_sel:DWORD
	v_and_b32_sdwa v216, v60, v108 dst_sel:DWORD dst_unused:UNUSED_PAD src0_sel:WORD_1 src1_sel:DWORD
	v_and_b32_sdwa v217, v61, v108 dst_sel:DWORD dst_unused:UNUSED_PAD src0_sel:WORD_1 src1_sel:DWORD
	v_and_b32_sdwa v218, v62, v108 dst_sel:DWORD dst_unused:UNUSED_PAD src0_sel:WORD_1 src1_sel:DWORD
	v_and_b32_sdwa v219, v63, v108 dst_sel:DWORD dst_unused:UNUSED_PAD src0_sel:WORD_1 src1_sel:DWORD
	v_add3_u32 v204, v56, v212, s66
	v_add3_u32 v205, v57, v213, s66
	v_add3_u32 v206, v58, v214, s66
	v_add3_u32 v207, v59, v215, s66
	v_add3_u32 v208, v60, v216, s66
	v_add3_u32 v209, v61, v217, s66
	v_add3_u32 v210, v62, v218, s66
	v_add3_u32 v211, v63, v219, s66
	v_and_b32_e32 v205, 0xffff0000, v205
	v_and_b32_e32 v207, 0xffff0000, v207
	v_and_b32_e32 v209, 0xffff0000, v209
	v_and_b32_e32 v211, 0xffff0000, v211
	v_or_b32_sdwa v224, v205, v204 dst_sel:DWORD dst_unused:UNUSED_PAD src0_sel:DWORD src1_sel:WORD_1
	v_or_b32_sdwa v225, v207, v206 dst_sel:DWORD dst_unused:UNUSED_PAD src0_sel:DWORD src1_sel:WORD_1
	v_or_b32_sdwa v226, v209, v208 dst_sel:DWORD dst_unused:UNUSED_PAD src0_sel:DWORD src1_sel:WORD_1
	v_or_b32_sdwa v227, v211, v210 dst_sel:DWORD dst_unused:UNUSED_PAD src0_sel:DWORD src1_sel:WORD_1
	s_nop 1
	v_permlane16_swap_b32_e32 v224, v226
	v_permlane16_swap_b32_e32 v225, v227
	global_store_dwordx4 v231, v[224:227], s[84:85] offset:64
	s_cmp_eq_u32 s95, 1
	s_cbranch_scc0 .Lgp9_single
	s_load_dwordx2 s[84:85], s[0:1], 0xa0
	v_lshrrev_b32_e32 v232, 1, v168
	v_and_b32_e32 v232, 0x1c0, v232
	v_and_b32_e32 v233, 15, v168
	v_or_b32_e32 v232, v232, v233
	v_lshl_add_u32 v232, s50, 7, v232
	v_lshlrev_b32_e32 v232, 12, v232
	v_bfe_u32 v233, v168, 4, 2
	v_lshlrev_b32_e32 v229, 3, v233
	v_and_b32_e32 v233, 1, v233
	v_mul_u32_u24_e32 v233, 24, v233
	v_add3_u32 v232, v232, v233, v229
	v_bfe_u32 v233, v168, 6, 1
	s_lshl_b32 s87, s83, 8
	v_lshl_add_u32 v228, v233, 7, v232
	v_add_u32_e32 v228, s87, v228
	v_add_u32_e32 v229, 0x10000, v228
	v_add_u32_e32 v230, 0x20000, v228
	v_add_u32_e32 v231, 0x30000, v228
	s_waitcnt lgkmcnt(0)
	v_and_b32_sdwa v212, v116, v108 dst_sel:DWORD dst_unused:UNUSED_PAD src0_sel:WORD_1 src1_sel:DWORD
	v_and_b32_sdwa v213, v117, v108 dst_sel:DWORD dst_unused:UNUSED_PAD src0_sel:WORD_1 src1_sel:DWORD
	v_and_b32_sdwa v214, v118, v108 dst_sel:DWORD dst_unused:UNUSED_PAD src0_sel:WORD_1 src1_sel:DWORD
	v_and_b32_sdwa v215, v119, v108 dst_sel:DWORD dst_unused:UNUSED_PAD src0_sel:WORD_1 src1_sel:DWORD
	v_and_b32_sdwa v216, v120, v108 dst_sel:DWORD dst_unused:UNUSED_PAD src0_sel:WORD_1 src1_sel:DWORD
	v_and_b32_sdwa v217, v121, v108 dst_sel:DWORD dst_unused:UNUSED_PAD src0_sel:WORD_1 src1_sel:DWORD
	v_and_b32_sdwa v218, v122, v108 dst_sel:DWORD dst_unused:UNUSED_PAD src0_sel:WORD_1 src1_sel:DWORD
	v_and_b32_sdwa v219, v123, v108 dst_sel:DWORD dst_unused:UNUSED_PAD src0_sel:WORD_1 src1_sel:DWORD
	v_add3_u32 v204, v116, v212, s66
	v_add3_u32 v205, v117, v213, s66
	v_add3_u32 v206, v118, v214, s66
	v_add3_u32 v207, v119, v215, s66
	v_add3_u32 v208, v120, v216, s66
	v_add3_u32 v209, v121, v217, s66
	v_add3_u32 v210, v122, v218, s66
	v_add3_u32 v211, v123, v219, s66
	v_and_b32_e32 v205, 0xffff0000, v205
	v_and_b32_e32 v207, 0xffff0000, v207
	v_and_b32_e32 v209, 0xffff0000, v209
	v_and_b32_e32 v211, 0xffff0000, v211
	v_or_b32_sdwa v220, v205, v204 dst_sel:DWORD dst_unused:UNUSED_PAD src0_sel:DWORD src1_sel:WORD_1
	v_or_b32_sdwa v221, v207, v206 dst_sel:DWORD dst_unused:UNUSED_PAD src0_sel:DWORD src1_sel:WORD_1
	v_or_b32_sdwa v222, v209, v208 dst_sel:DWORD dst_unused:UNUSED_PAD src0_sel:DWORD src1_sel:WORD_1
	v_or_b32_sdwa v223, v211, v210 dst_sel:DWORD dst_unused:UNUSED_PAD src0_sel:DWORD src1_sel:WORD_1
	s_nop 1
	v_permlane16_swap_b32_e32 v220, v222
	v_permlane16_swap_b32_e32 v221, v223
	global_store_dwordx4 v228, v[220:223], s[84:85]
	v_and_b32_sdwa v212, v124, v108 dst_sel:DWORD dst_unused:UNUSED_PAD src0_sel:WORD_1 src1_sel:DWORD
	v_and_b32_sdwa v213, v125, v108 dst_sel:DWORD dst_unused:UNUSED_PAD src0_sel:WORD_1 src1_sel:DWORD
	v_and_b32_sdwa v214, v126, v108 dst_sel:DWORD dst_unused:UNUSED_PAD src0_sel:WORD_1 src1_sel:DWORD
	v_and_b32_sdwa v215, v127, v108 dst_sel:DWORD dst_unused:UNUSED_PAD src0_sel:WORD_1 src1_sel:DWORD
	v_and_b32_sdwa v216, v128, v108 dst_sel:DWORD dst_unused:UNUSED_PAD src0_sel:WORD_1 src1_sel:DWORD
	v_and_b32_sdwa v217, v129, v108 dst_sel:DWORD dst_unused:UNUSED_PAD src0_sel:WORD_1 src1_sel:DWORD
	v_and_b32_sdwa v218, v130, v108 dst_sel:DWORD dst_unused:UNUSED_PAD src0_sel:WORD_1 src1_sel:DWORD
	v_and_b32_sdwa v219, v131, v108 dst_sel:DWORD dst_unused:UNUSED_PAD src0_sel:WORD_1 src1_sel:DWORD
	v_add3_u32 v204, v124, v212, s66
	v_add3_u32 v205, v125, v213, s66
	v_add3_u32 v206, v126, v214, s66
	v_add3_u32 v207, v127, v215, s66
	v_add3_u32 v208, v128, v216, s66
	v_add3_u32 v209, v129, v217, s66
	v_add3_u32 v210, v130, v218, s66
	v_add3_u32 v211, v131, v219, s66
	v_and_b32_e32 v205, 0xffff0000, v205
	v_and_b32_e32 v207, 0xffff0000, v207
	v_and_b32_e32 v209, 0xffff0000, v209
	v_and_b32_e32 v211, 0xffff0000, v211
	v_or_b32_sdwa v224, v205, v204 dst_sel:DWORD dst_unused:UNUSED_PAD src0_sel:DWORD src1_sel:WORD_1
	v_or_b32_sdwa v225, v207, v206 dst_sel:DWORD dst_unused:UNUSED_PAD src0_sel:DWORD src1_sel:WORD_1
	v_or_b32_sdwa v226, v209, v208 dst_sel:DWORD dst_unused:UNUSED_PAD src0_sel:DWORD src1_sel:WORD_1
	v_or_b32_sdwa v227, v211, v210 dst_sel:DWORD dst_unused:UNUSED_PAD src0_sel:DWORD src1_sel:WORD_1
	s_nop 1
	v_permlane16_swap_b32_e32 v224, v226
	v_permlane16_swap_b32_e32 v225, v227
	global_store_dwordx4 v228, v[224:227], s[84:85] offset:64
	v_and_b32_sdwa v212, v132, v108 dst_sel:DWORD dst_unused:UNUSED_PAD src0_sel:WORD_1 src1_sel:DWORD
	v_and_b32_sdwa v213, v133, v108 dst_sel:DWORD dst_unused:UNUSED_PAD src0_sel:WORD_1 src1_sel:DWORD
	v_and_b32_sdwa v214, v134, v108 dst_sel:DWORD dst_unused:UNUSED_PAD src0_sel:WORD_1 src1_sel:DWORD
	v_and_b32_sdwa v215, v135, v108 dst_sel:DWORD dst_unused:UNUSED_PAD src0_sel:WORD_1 src1_sel:DWORD
	v_and_b32_sdwa v216, v136, v108 dst_sel:DWORD dst_unused:UNUSED_PAD src0_sel:WORD_1 src1_sel:DWORD
	v_and_b32_sdwa v217, v137, v108 dst_sel:DWORD dst_unused:UNUSED_PAD src0_sel:WORD_1 src1_sel:DWORD
	v_and_b32_sdwa v218, v138, v108 dst_sel:DWORD dst_unused:UNUSED_PAD src0_sel:WORD_1 src1_sel:DWORD
	v_and_b32_sdwa v219, v139, v108 dst_sel:DWORD dst_unused:UNUSED_PAD src0_sel:WORD_1 src1_sel:DWORD
	v_add3_u32 v204, v132, v212, s66
	v_add3_u32 v205, v133, v213, s66
	v_add3_u32 v206, v134, v214, s66
	v_add3_u32 v207, v135, v215, s66
	v_add3_u32 v208, v136, v216, s66
	v_add3_u32 v209, v137, v217, s66
	v_add3_u32 v210, v138, v218, s66
	v_add3_u32 v211, v139, v219, s66
	v_and_b32_e32 v205, 0xffff0000, v205
	v_and_b32_e32 v207, 0xffff0000, v207
	v_and_b32_e32 v209, 0xffff0000, v209
	v_and_b32_e32 v211, 0xffff0000, v211
	v_or_b32_sdwa v220, v205, v204 dst_sel:DWORD dst_unused:UNUSED_PAD src0_sel:DWORD src1_sel:WORD_1
	v_or_b32_sdwa v221, v207, v206 dst_sel:DWORD dst_unused:UNUSED_PAD src0_sel:DWORD src1_sel:WORD_1
	v_or_b32_sdwa v222, v209, v208 dst_sel:DWORD dst_unused:UNUSED_PAD src0_sel:DWORD src1_sel:WORD_1
	v_or_b32_sdwa v223, v211, v210 dst_sel:DWORD dst_unused:UNUSED_PAD src0_sel:DWORD src1_sel:WORD_1
	s_nop 1
	v_permlane16_swap_b32_e32 v220, v222
	v_permlane16_swap_b32_e32 v221, v223
	global_store_dwordx4 v229, v[220:223], s[84:85]
	v_and_b32_sdwa v212, v140, v108 dst_sel:DWORD dst_unused:UNUSED_PAD src0_sel:WORD_1 src1_sel:DWORD
	v_and_b32_sdwa v213, v141, v108 dst_sel:DWORD dst_unused:UNUSED_PAD src0_sel:WORD_1 src1_sel:DWORD
	v_and_b32_sdwa v214, v142, v108 dst_sel:DWORD dst_unused:UNUSED_PAD src0_sel:WORD_1 src1_sel:DWORD
	v_and_b32_sdwa v215, v143, v108 dst_sel:DWORD dst_unused:UNUSED_PAD src0_sel:WORD_1 src1_sel:DWORD
	v_and_b32_sdwa v216, v148, v108 dst_sel:DWORD dst_unused:UNUSED_PAD src0_sel:WORD_1 src1_sel:DWORD
	v_and_b32_sdwa v217, v149, v108 dst_sel:DWORD dst_unused:UNUSED_PAD src0_sel:WORD_1 src1_sel:DWORD
	v_and_b32_sdwa v218, v150, v108 dst_sel:DWORD dst_unused:UNUSED_PAD src0_sel:WORD_1 src1_sel:DWORD
	v_and_b32_sdwa v219, v151, v108 dst_sel:DWORD dst_unused:UNUSED_PAD src0_sel:WORD_1 src1_sel:DWORD
	v_add3_u32 v204, v140, v212, s66
	v_add3_u32 v205, v141, v213, s66
	v_add3_u32 v206, v142, v214, s66
	v_add3_u32 v207, v143, v215, s66
	v_add3_u32 v208, v148, v216, s66
	v_add3_u32 v209, v149, v217, s66
	v_add3_u32 v210, v150, v218, s66
	v_add3_u32 v211, v151, v219, s66
	v_and_b32_e32 v205, 0xffff0000, v205
	v_and_b32_e32 v207, 0xffff0000, v207
	v_and_b32_e32 v209, 0xffff0000, v209
	v_and_b32_e32 v211, 0xffff0000, v211
	v_or_b32_sdwa v224, v205, v204 dst_sel:DWORD dst_unused:UNUSED_PAD src0_sel:DWORD src1_sel:WORD_1
	v_or_b32_sdwa v225, v207, v206 dst_sel:DWORD dst_unused:UNUSED_PAD src0_sel:DWORD src1_sel:WORD_1
	v_or_b32_sdwa v226, v209, v208 dst_sel:DWORD dst_unused:UNUSED_PAD src0_sel:DWORD src1_sel:WORD_1
	v_or_b32_sdwa v227, v211, v210 dst_sel:DWORD dst_unused:UNUSED_PAD src0_sel:DWORD src1_sel:WORD_1
	s_nop 1
	v_permlane16_swap_b32_e32 v224, v226
	v_permlane16_swap_b32_e32 v225, v227
	global_store_dwordx4 v229, v[224:227], s[84:85] offset:64
	v_and_b32_sdwa v212, v152, v108 dst_sel:DWORD dst_unused:UNUSED_PAD src0_sel:WORD_1 src1_sel:DWORD
	v_and_b32_sdwa v213, v153, v108 dst_sel:DWORD dst_unused:UNUSED_PAD src0_sel:WORD_1 src1_sel:DWORD
	v_and_b32_sdwa v214, v154, v108 dst_sel:DWORD dst_unused:UNUSED_PAD src0_sel:WORD_1 src1_sel:DWORD
	v_and_b32_sdwa v215, v155, v108 dst_sel:DWORD dst_unused:UNUSED_PAD src0_sel:WORD_1 src1_sel:DWORD
	v_and_b32_sdwa v216, v156, v108 dst_sel:DWORD dst_unused:UNUSED_PAD src0_sel:WORD_1 src1_sel:DWORD
	v_and_b32_sdwa v217, v157, v108 dst_sel:DWORD dst_unused:UNUSED_PAD src0_sel:WORD_1 src1_sel:DWORD
	v_and_b32_sdwa v218, v158, v108 dst_sel:DWORD dst_unused:UNUSED_PAD src0_sel:WORD_1 src1_sel:DWORD
	v_and_b32_sdwa v219, v159, v108 dst_sel:DWORD dst_unused:UNUSED_PAD src0_sel:WORD_1 src1_sel:DWORD
	v_add3_u32 v204, v152, v212, s66
	v_add3_u32 v205, v153, v213, s66
	v_add3_u32 v206, v154, v214, s66
	v_add3_u32 v207, v155, v215, s66
	v_add3_u32 v208, v156, v216, s66
	v_add3_u32 v209, v157, v217, s66
	v_add3_u32 v210, v158, v218, s66
	v_add3_u32 v211, v159, v219, s66
	v_and_b32_e32 v205, 0xffff0000, v205
	v_and_b32_e32 v207, 0xffff0000, v207
	v_and_b32_e32 v209, 0xffff0000, v209
	v_and_b32_e32 v211, 0xffff0000, v211
	v_or_b32_sdwa v220, v205, v204 dst_sel:DWORD dst_unused:UNUSED_PAD src0_sel:DWORD src1_sel:WORD_1
	v_or_b32_sdwa v221, v207, v206 dst_sel:DWORD dst_unused:UNUSED_PAD src0_sel:DWORD src1_sel:WORD_1
	v_or_b32_sdwa v222, v209, v208 dst_sel:DWORD dst_unused:UNUSED_PAD src0_sel:DWORD src1_sel:WORD_1
	v_or_b32_sdwa v223, v211, v210 dst_sel:DWORD dst_unused:UNUSED_PAD src0_sel:DWORD src1_sel:WORD_1
	s_nop 1
	v_permlane16_swap_b32_e32 v220, v222
	v_permlane16_swap_b32_e32 v221, v223
	global_store_dwordx4 v230, v[220:223], s[84:85]
	v_and_b32_sdwa v212, v160, v108 dst_sel:DWORD dst_unused:UNUSED_PAD src0_sel:WORD_1 src1_sel:DWORD
	v_and_b32_sdwa v213, v161, v108 dst_sel:DWORD dst_unused:UNUSED_PAD src0_sel:WORD_1 src1_sel:DWORD
	v_and_b32_sdwa v214, v162, v108 dst_sel:DWORD dst_unused:UNUSED_PAD src0_sel:WORD_1 src1_sel:DWORD
	v_and_b32_sdwa v215, v163, v108 dst_sel:DWORD dst_unused:UNUSED_PAD src0_sel:WORD_1 src1_sel:DWORD
	v_and_b32_sdwa v216, v172, v108 dst_sel:DWORD dst_unused:UNUSED_PAD src0_sel:WORD_1 src1_sel:DWORD
	v_and_b32_sdwa v217, v173, v108 dst_sel:DWORD dst_unused:UNUSED_PAD src0_sel:WORD_1 src1_sel:DWORD
	v_and_b32_sdwa v218, v174, v108 dst_sel:DWORD dst_unused:UNUSED_PAD src0_sel:WORD_1 src1_sel:DWORD
	v_and_b32_sdwa v219, v175, v108 dst_sel:DWORD dst_unused:UNUSED_PAD src0_sel:WORD_1 src1_sel:DWORD
	v_add3_u32 v204, v160, v212, s66
	v_add3_u32 v205, v161, v213, s66
	v_add3_u32 v206, v162, v214, s66
	v_add3_u32 v207, v163, v215, s66
	v_add3_u32 v208, v172, v216, s66
	v_add3_u32 v209, v173, v217, s66
	v_add3_u32 v210, v174, v218, s66
	v_add3_u32 v211, v175, v219, s66
	v_and_b32_e32 v205, 0xffff0000, v205
	v_and_b32_e32 v207, 0xffff0000, v207
	v_and_b32_e32 v209, 0xffff0000, v209
	v_and_b32_e32 v211, 0xffff0000, v211
	v_or_b32_sdwa v224, v205, v204 dst_sel:DWORD dst_unused:UNUSED_PAD src0_sel:DWORD src1_sel:WORD_1
	v_or_b32_sdwa v225, v207, v206 dst_sel:DWORD dst_unused:UNUSED_PAD src0_sel:DWORD src1_sel:WORD_1
	v_or_b32_sdwa v226, v209, v208 dst_sel:DWORD dst_unused:UNUSED_PAD src0_sel:DWORD src1_sel:WORD_1
	v_or_b32_sdwa v227, v211, v210 dst_sel:DWORD dst_unused:UNUSED_PAD src0_sel:DWORD src1_sel:WORD_1
	s_nop 1
	v_permlane16_swap_b32_e32 v224, v226
	v_permlane16_swap_b32_e32 v225, v227
	global_store_dwordx4 v230, v[224:227], s[84:85] offset:64
	v_and_b32_sdwa v212, v176, v108 dst_sel:DWORD dst_unused:UNUSED_PAD src0_sel:WORD_1 src1_sel:DWORD
	v_and_b32_sdwa v213, v177, v108 dst_sel:DWORD dst_unused:UNUSED_PAD src0_sel:WORD_1 src1_sel:DWORD
	v_and_b32_sdwa v214, v178, v108 dst_sel:DWORD dst_unused:UNUSED_PAD src0_sel:WORD_1 src1_sel:DWORD
	v_and_b32_sdwa v215, v179, v108 dst_sel:DWORD dst_unused:UNUSED_PAD src0_sel:WORD_1 src1_sel:DWORD
	v_and_b32_sdwa v216, v180, v108 dst_sel:DWORD dst_unused:UNUSED_PAD src0_sel:WORD_1 src1_sel:DWORD
	v_and_b32_sdwa v217, v181, v108 dst_sel:DWORD dst_unused:UNUSED_PAD src0_sel:WORD_1 src1_sel:DWORD
	v_and_b32_sdwa v218, v182, v108 dst_sel:DWORD dst_unused:UNUSED_PAD src0_sel:WORD_1 src1_sel:DWORD
	v_and_b32_sdwa v219, v183, v108 dst_sel:DWORD dst_unused:UNUSED_PAD src0_sel:WORD_1 src1_sel:DWORD
	v_add3_u32 v204, v176, v212, s66
	v_add3_u32 v205, v177, v213, s66
	v_add3_u32 v206, v178, v214, s66
	v_add3_u32 v207, v179, v215, s66
	v_add3_u32 v208, v180, v216, s66
	v_add3_u32 v209, v181, v217, s66
	v_add3_u32 v210, v182, v218, s66
	v_add3_u32 v211, v183, v219, s66
	v_and_b32_e32 v205, 0xffff0000, v205
	v_and_b32_e32 v207, 0xffff0000, v207
	v_and_b32_e32 v209, 0xffff0000, v209
	v_and_b32_e32 v211, 0xffff0000, v211
	v_or_b32_sdwa v220, v205, v204 dst_sel:DWORD dst_unused:UNUSED_PAD src0_sel:DWORD src1_sel:WORD_1
	v_or_b32_sdwa v221, v207, v206 dst_sel:DWORD dst_unused:UNUSED_PAD src0_sel:DWORD src1_sel:WORD_1
	v_or_b32_sdwa v222, v209, v208 dst_sel:DWORD dst_unused:UNUSED_PAD src0_sel:DWORD src1_sel:WORD_1
	v_or_b32_sdwa v223, v211, v210 dst_sel:DWORD dst_unused:UNUSED_PAD src0_sel:DWORD src1_sel:WORD_1
	s_nop 1
	v_permlane16_swap_b32_e32 v220, v222
	v_permlane16_swap_b32_e32 v221, v223
	global_store_dwordx4 v231, v[220:223], s[84:85]
	v_and_b32_sdwa v212, v184, v108 dst_sel:DWORD dst_unused:UNUSED_PAD src0_sel:WORD_1 src1_sel:DWORD
	v_and_b32_sdwa v213, v185, v108 dst_sel:DWORD dst_unused:UNUSED_PAD src0_sel:WORD_1 src1_sel:DWORD
	v_and_b32_sdwa v214, v186, v108 dst_sel:DWORD dst_unused:UNUSED_PAD src0_sel:WORD_1 src1_sel:DWORD
	v_and_b32_sdwa v215, v187, v108 dst_sel:DWORD dst_unused:UNUSED_PAD src0_sel:WORD_1 src1_sel:DWORD
	v_and_b32_sdwa v216, v188, v108 dst_sel:DWORD dst_unused:UNUSED_PAD src0_sel:WORD_1 src1_sel:DWORD
	v_and_b32_sdwa v217, v189, v108 dst_sel:DWORD dst_unused:UNUSED_PAD src0_sel:WORD_1 src1_sel:DWORD
	v_and_b32_sdwa v218, v190, v108 dst_sel:DWORD dst_unused:UNUSED_PAD src0_sel:WORD_1 src1_sel:DWORD
	v_and_b32_sdwa v219, v191, v108 dst_sel:DWORD dst_unused:UNUSED_PAD src0_sel:WORD_1 src1_sel:DWORD
	v_add3_u32 v204, v184, v212, s66
	v_add3_u32 v205, v185, v213, s66
	v_add3_u32 v206, v186, v214, s66
	v_add3_u32 v207, v187, v215, s66
	v_add3_u32 v208, v188, v216, s66
	v_add3_u32 v209, v189, v217, s66
	v_add3_u32 v210, v190, v218, s66
	v_add3_u32 v211, v191, v219, s66
	v_and_b32_e32 v205, 0xffff0000, v205
	v_and_b32_e32 v207, 0xffff0000, v207
	v_and_b32_e32 v209, 0xffff0000, v209
	v_and_b32_e32 v211, 0xffff0000, v211
	v_or_b32_sdwa v224, v205, v204 dst_sel:DWORD dst_unused:UNUSED_PAD src0_sel:DWORD src1_sel:WORD_1
	v_or_b32_sdwa v225, v207, v206 dst_sel:DWORD dst_unused:UNUSED_PAD src0_sel:DWORD src1_sel:WORD_1
	v_or_b32_sdwa v226, v209, v208 dst_sel:DWORD dst_unused:UNUSED_PAD src0_sel:DWORD src1_sel:WORD_1
	v_or_b32_sdwa v227, v211, v210 dst_sel:DWORD dst_unused:UNUSED_PAD src0_sel:DWORD src1_sel:WORD_1
	s_nop 1
	v_permlane16_swap_b32_e32 v224, v226
	v_permlane16_swap_b32_e32 v225, v227
	global_store_dwordx4 v231, v[224:227], s[84:85] offset:64
	s_add_i32 s61, s61, s60
.Lgp9_single:
	s_mov_b32 s95, 0
	s_add_i32 s61, s61, s60
	s_cmp_ge_i32 s61, s62
	s_cbranch_scc0 .LBB0_660
